# mixer B compressed branch: K/V^T of the compressed keys staged once per unit in LDS (coalesced loads, ds_read_b128 fragments) instead of per-wave global gathers; residual epilogues of P3/P12 restructu
# speedup vs baseline: 1.0082x; 1.0068x over previous
.LBB0_112:
	s_lshl_b32 s22, s52, 8
	v_mbcnt_lo_u32_b32 v129, -1, 0
	v_mbcnt_hi_u32_b32 v129, -1, v129
	s_add_i32 s22, s22, s39
	v_and_or_b32 v128, v129, 15, s22
	s_lshl_b32 s22, s53, 8
	v_ashrrev_i32_e32 v129, 1, v129
	v_and_b32_e32 v129, -8, v129
	s_or_b32 s22, s22, s40
	v_add_u32_e32 v130, s22, v129
	v_ashrrev_i32_e32 v129, 31, v128
	v_lshlrev_b64 v[128:129], 12, v[128:129]
	v_ashrrev_i32_e32 v131, 31, v130
	v_lshl_add_u64 v[132:133], s[6:7], 0, v[128:129]
	v_lshlrev_b64 v[130:131], 2, v[130:131]
	v_lshl_add_u64 v[168:169], v[132:133], 0, v[130:131]
	v_lshl_add_u64 v[128:129], s[60:61], 0, v[128:129]
	v_lshl_add_u64 v[170:171], v[128:129], 0, v[130:131]
	s_mov_b64 s[8:9], 0x80000
	global_load_dwordx4 v[174:177], v[168:169], off
	global_load_dwordx4 v[178:181], v[168:169], off offset:16
	global_load_dwordx4 v[182:185], v[168:169], off offset:512
	global_load_dwordx4 v[186:189], v[168:169], off offset:528
	v_add_co_u32_e32 v128, vcc, s94, v168
	v_addc_co_u32_e32 v129, vcc, 0, v169, vcc
	global_load_dwordx4 v[190:193], v[128:129], off
	global_load_dwordx4 v[194:197], v[128:129], off offset:16
	global_load_dwordx4 v[198:201], v[128:129], off offset:512
	global_load_dwordx4 v[216:219], v[128:129], off offset:528
	v_add_co_u32_e32 v128, vcc, s0, v168
	v_addc_co_u32_e32 v129, vcc, 0, v169, vcc
	global_load_dwordx4 v[220:223], v[128:129], off
	global_load_dwordx4 v[154:157], v[128:129], off offset:16
	global_load_dwordx4 v[150:153], v[128:129], off offset:512
	global_load_dwordx4 v[146:149], v[128:129], off offset:528
	v_add_co_u32_e32 v128, vcc, s1, v168
	v_addc_co_u32_e32 v129, vcc, 0, v169, vcc
	global_load_dwordx4 v[142:145], v[128:129], off
	global_load_dwordx4 v[138:141], v[128:129], off offset:16
	global_load_dwordx4 v[132:135], v[128:129], off offset:512
	s_nop 0
	global_load_dwordx4 v[128:131], v[128:129], off offset:528
	s_waitcnt vmcnt(0)
	v_pk_fma_f32 v[124:125], v[124:125], 0.5, v[174:175] op_sel_hi:[1,0,1]
	v_pk_fma_f32 v[126:127], v[126:127], 0.5, v[176:177] op_sel_hi:[1,0,1]
	v_pk_fma_f32 v[120:121], v[120:121], 0.5, v[178:179] op_sel_hi:[1,0,1]
	v_pk_fma_f32 v[122:123], v[122:123], 0.5, v[180:181] op_sel_hi:[1,0,1]
	v_pk_fma_f32 v[112:113], v[112:113], 0.5, v[182:183] op_sel_hi:[1,0,1]
	v_pk_fma_f32 v[114:115], v[114:115], 0.5, v[184:185] op_sel_hi:[1,0,1]
	v_pk_fma_f32 v[108:109], v[108:109], 0.5, v[186:187] op_sel_hi:[1,0,1]
	v_pk_fma_f32 v[110:111], v[110:111], 0.5, v[188:189] op_sel_hi:[1,0,1]
	v_pk_fma_f32 v[116:117], v[116:117], 0.5, v[190:191] op_sel_hi:[1,0,1]
	v_pk_fma_f32 v[118:119], v[118:119], 0.5, v[192:193] op_sel_hi:[1,0,1]
	v_pk_fma_f32 v[104:105], v[104:105], 0.5, v[194:195] op_sel_hi:[1,0,1]
	v_pk_fma_f32 v[106:107], v[106:107], 0.5, v[196:197] op_sel_hi:[1,0,1]
	v_pk_fma_f32 v[96:97], v[96:97], 0.5, v[198:199] op_sel_hi:[1,0,1]
	v_pk_fma_f32 v[98:99], v[98:99], 0.5, v[200:201] op_sel_hi:[1,0,1]
	v_pk_fma_f32 v[92:93], v[92:93], 0.5, v[216:217] op_sel_hi:[1,0,1]
	v_pk_fma_f32 v[94:95], v[94:95], 0.5, v[218:219] op_sel_hi:[1,0,1]
	v_pk_fma_f32 v[100:101], v[100:101], 0.5, v[220:221] op_sel_hi:[1,0,1]
	v_pk_fma_f32 v[102:103], v[102:103], 0.5, v[222:223] op_sel_hi:[1,0,1]
	v_pk_fma_f32 v[88:89], v[88:89], 0.5, v[154:155] op_sel_hi:[1,0,1]
	v_pk_fma_f32 v[90:91], v[90:91], 0.5, v[156:157] op_sel_hi:[1,0,1]
	v_pk_fma_f32 v[84:85], v[84:85], 0.5, v[150:151] op_sel_hi:[1,0,1]
	v_pk_fma_f32 v[86:87], v[86:87], 0.5, v[152:153] op_sel_hi:[1,0,1]
	v_pk_fma_f32 v[80:81], v[80:81], 0.5, v[146:147] op_sel_hi:[1,0,1]
	v_pk_fma_f32 v[82:83], v[82:83], 0.5, v[148:149] op_sel_hi:[1,0,1]
	v_pk_fma_f32 v[76:77], v[76:77], 0.5, v[142:143] op_sel_hi:[1,0,1]
	v_pk_fma_f32 v[78:79], v[78:79], 0.5, v[144:145] op_sel_hi:[1,0,1]
	v_pk_fma_f32 v[72:73], v[72:73], 0.5, v[138:139] op_sel_hi:[1,0,1]
	v_pk_fma_f32 v[74:75], v[74:75], 0.5, v[140:141] op_sel_hi:[1,0,1]
	v_pk_fma_f32 v[68:69], v[68:69], 0.5, v[132:133] op_sel_hi:[1,0,1]
	v_pk_fma_f32 v[70:71], v[70:71], 0.5, v[134:135] op_sel_hi:[1,0,1]
	v_pk_fma_f32 v[64:65], v[64:65], 0.5, v[128:129] op_sel_hi:[1,0,1]
	v_pk_fma_f32 v[66:67], v[66:67], 0.5, v[130:131] op_sel_hi:[1,0,1]
	v_lshl_add_u64 v[128:129], v[168:169], 0, s[8:9]
	global_load_dwordx4 v[174:177], v[128:129], off
	global_load_dwordx4 v[178:181], v[128:129], off offset:16
	global_load_dwordx4 v[182:185], v[128:129], off offset:512
	global_load_dwordx4 v[186:189], v[128:129], off offset:528
	v_add_co_u32_e32 v128, vcc, s94, v128
	v_addc_co_u32_e32 v129, vcc, 0, v129, vcc
	global_load_dwordx4 v[190:193], v[128:129], off
	global_load_dwordx4 v[194:197], v[128:129], off offset:16
	global_load_dwordx4 v[198:201], v[128:129], off offset:512
	global_load_dwordx4 v[216:219], v[128:129], off offset:528
	v_add_co_u32_e32 v128, vcc, s94, v128
	v_addc_co_u32_e32 v129, vcc, 0, v129, vcc
	global_load_dwordx4 v[220:223], v[128:129], off
	global_load_dwordx4 v[154:157], v[128:129], off offset:16
	global_load_dwordx4 v[150:153], v[128:129], off offset:512
	global_load_dwordx4 v[146:149], v[128:129], off offset:528
	v_add_co_u32_e32 v128, vcc, s94, v128
	v_addc_co_u32_e32 v129, vcc, 0, v129, vcc
	global_load_dwordx4 v[142:145], v[128:129], off
	global_load_dwordx4 v[138:141], v[128:129], off offset:16
	global_load_dwordx4 v[132:135], v[128:129], off offset:512
	s_nop 0
	global_load_dwordx4 v[128:131], v[128:129], off offset:528
	global_store_dwordx4 v[170:171], v[124:127], off
	global_store_dwordx4 v[170:171], v[120:123], off offset:16
	global_store_dwordx4 v[170:171], v[112:115], off offset:512
	global_store_dwordx4 v[170:171], v[108:111], off offset:528
	v_add_co_u32_e32 v124, vcc, s94, v170
	v_addc_co_u32_e32 v125, vcc, 0, v171, vcc
	global_store_dwordx4 v[124:125], v[116:119], off
	global_store_dwordx4 v[124:125], v[104:107], off offset:16
	global_store_dwordx4 v[124:125], v[96:99], off offset:512
	global_store_dwordx4 v[124:125], v[92:95], off offset:528
	v_add_co_u32_e32 v126, vcc, s0, v170
	v_addc_co_u32_e32 v127, vcc, 0, v171, vcc
	global_store_dwordx4 v[126:127], v[100:103], off
	global_store_dwordx4 v[126:127], v[88:91], off offset:16
	global_store_dwordx4 v[126:127], v[84:87], off offset:512
	global_store_dwordx4 v[126:127], v[80:83], off offset:528
	v_add_co_u32_e32 v120, vcc, s1, v170
	v_addc_co_u32_e32 v121, vcc, 0, v171, vcc
	global_store_dwordx4 v[120:121], v[76:79], off
	global_store_dwordx4 v[120:121], v[72:75], off offset:16
	global_store_dwordx4 v[120:121], v[68:71], off offset:512
	global_store_dwordx4 v[120:121], v[64:67], off offset:528
	v_lshl_add_u64 v[112:113], v[170:171], 0, s[8:9]
	v_add_co_u32_e32 v114, vcc, s94, v112
	v_addc_co_u32_e32 v115, vcc, 0, v113, vcc
	v_add_co_u32_e32 v108, vcc, s0, v112
	v_addc_co_u32_e32 v109, vcc, 0, v113, vcc
	v_add_co_u32_e32 v110, vcc, s1, v112
	v_addc_co_u32_e32 v111, vcc, 0, v113, vcc
	s_waitcnt vmcnt(16)
	v_pk_fma_f32 v[60:61], v[60:61], 0.5, v[174:175] op_sel_hi:[1,0,1]
	v_pk_fma_f32 v[62:63], v[62:63], 0.5, v[176:177] op_sel_hi:[1,0,1]
	v_pk_fma_f32 v[56:57], v[56:57], 0.5, v[178:179] op_sel_hi:[1,0,1]
	v_pk_fma_f32 v[58:59], v[58:59], 0.5, v[180:181] op_sel_hi:[1,0,1]
	v_pk_fma_f32 v[48:49], v[48:49], 0.5, v[182:183] op_sel_hi:[1,0,1]
	v_pk_fma_f32 v[50:51], v[50:51], 0.5, v[184:185] op_sel_hi:[1,0,1]
	v_pk_fma_f32 v[44:45], v[44:45], 0.5, v[186:187] op_sel_hi:[1,0,1]
	v_pk_fma_f32 v[46:47], v[46:47], 0.5, v[188:189] op_sel_hi:[1,0,1]
	v_pk_fma_f32 v[52:53], v[52:53], 0.5, v[190:191] op_sel_hi:[1,0,1]
	v_pk_fma_f32 v[54:55], v[54:55], 0.5, v[192:193] op_sel_hi:[1,0,1]
	v_pk_fma_f32 v[40:41], v[40:41], 0.5, v[194:195] op_sel_hi:[1,0,1]
	v_pk_fma_f32 v[42:43], v[42:43], 0.5, v[196:197] op_sel_hi:[1,0,1]
	v_pk_fma_f32 v[32:33], v[32:33], 0.5, v[198:199] op_sel_hi:[1,0,1]
	v_pk_fma_f32 v[34:35], v[34:35], 0.5, v[200:201] op_sel_hi:[1,0,1]
	v_pk_fma_f32 v[28:29], v[28:29], 0.5, v[216:217] op_sel_hi:[1,0,1]
	v_pk_fma_f32 v[30:31], v[30:31], 0.5, v[218:219] op_sel_hi:[1,0,1]
	v_pk_fma_f32 v[36:37], v[36:37], 0.5, v[220:221] op_sel_hi:[1,0,1]
	v_pk_fma_f32 v[38:39], v[38:39], 0.5, v[222:223] op_sel_hi:[1,0,1]
	v_pk_fma_f32 v[24:25], v[24:25], 0.5, v[154:155] op_sel_hi:[1,0,1]
	v_pk_fma_f32 v[26:27], v[26:27], 0.5, v[156:157] op_sel_hi:[1,0,1]
	v_pk_fma_f32 v[16:17], v[16:17], 0.5, v[150:151] op_sel_hi:[1,0,1]
	v_pk_fma_f32 v[18:19], v[18:19], 0.5, v[152:153] op_sel_hi:[1,0,1]
	v_pk_fma_f32 v[12:13], v[12:13], 0.5, v[146:147] op_sel_hi:[1,0,1]
	v_pk_fma_f32 v[14:15], v[14:15], 0.5, v[148:149] op_sel_hi:[1,0,1]
	v_pk_fma_f32 v[20:21], v[20:21], 0.5, v[142:143] op_sel_hi:[1,0,1]
	v_pk_fma_f32 v[22:23], v[22:23], 0.5, v[144:145] op_sel_hi:[1,0,1]
	v_pk_fma_f32 v[8:9], v[8:9], 0.5, v[138:139] op_sel_hi:[1,0,1]
	v_pk_fma_f32 v[10:11], v[10:11], 0.5, v[140:141] op_sel_hi:[1,0,1]
	v_pk_fma_f32 v[4:5], v[4:5], 0.5, v[132:133] op_sel_hi:[1,0,1]
	v_pk_fma_f32 v[6:7], v[6:7], 0.5, v[134:135] op_sel_hi:[1,0,1]
	v_pk_fma_f32 v[0:1], v[0:1], 0.5, v[128:129] op_sel_hi:[1,0,1]
	v_pk_fma_f32 v[2:3], v[2:3], 0.5, v[130:131] op_sel_hi:[1,0,1]
	global_store_dwordx4 v[112:113], v[60:63], off
	global_store_dwordx4 v[112:113], v[56:59], off offset:16
	global_store_dwordx4 v[112:113], v[48:51], off offset:512
	global_store_dwordx4 v[112:113], v[44:47], off offset:528
	global_store_dwordx4 v[114:115], v[52:55], off
	global_store_dwordx4 v[114:115], v[40:43], off offset:16
	global_store_dwordx4 v[114:115], v[32:35], off offset:512
	global_store_dwordx4 v[114:115], v[28:31], off offset:528
	global_store_dwordx4 v[108:109], v[36:39], off
	global_store_dwordx4 v[108:109], v[24:27], off offset:16
	global_store_dwordx4 v[108:109], v[16:19], off offset:512
	global_store_dwordx4 v[108:109], v[12:15], off offset:528
	global_store_dwordx4 v[110:111], v[20:23], off
	global_store_dwordx4 v[110:111], v[8:11], off offset:16
	global_store_dwordx4 v[110:111], v[4:7], off offset:512
	global_store_dwordx4 v[110:111], v[0:3], off offset:528
	s_mov_b64 s[22:23], -1
	s_and_b64 vcc, exec, s[2:3]
	s_cbranch_vccnz .LBB0_97
	s_andn2_b64 vcc, exec, s[66:67]
	s_cbranch_vccnz .LBB0_96
	s_barrier
	s_branch .LBB0_96

.LBB0_414:
	v_readlane_b32 s100, v255, 33
	v_readlane_b32 s101, v255, 34
	v_add_u32_e32 v172, s63, v115
	v_lshlrev_b32_e32 v173, 4, v172
	v_add_u32_e32 v174, 0x2000, v173
	v_add_u32_e32 v175, 0x4000, v173
	v_add_u32_e32 v176, 0x6000, v173
	s_nop 0
	global_load_dwordx4 v[140:143], v173, s[42:43]
	global_load_dwordx4 v[144:147], v174, s[42:43]
	global_load_dwordx4 v[148:151], v175, s[42:43]
	global_load_dwordx4 v[152:155], v176, s[42:43]
	global_load_dwordx4 v[156:159], v173, s[100:101]
	global_load_dwordx4 v[160:163], v174, s[100:101]
	global_load_dwordx4 v[164:167], v175, s[100:101]
	global_load_dwordx4 v[168:171], v176, s[100:101]
	v_lshrrev_b32_e32 v177, 3, v172
	v_and_b32_e32 v179, 7, v172
	v_mul_u32_u24_e32 v177, 0xa0, v177
	v_lshl_add_u32 v177, v179, 4, v177
	v_add_u32_e32 v177, 0x4000, v177
	v_lshrrev_b32_e32 v178, 5, v172
	v_and_b32_e32 v179, 31, v172
	v_mul_u32_u24_e32 v178, 0x220, v178
	v_lshl_add_u32 v178, v179, 4, v178
	v_add_u32_e32 v178, 0xe000, v178
	v_and_b32_e32 v179, 15, v115
	v_lshrrev_b32_e32 v180, 4, v115
	v_mul_u32_u24_e32 v252, 0xa0, v179
	v_lshl_add_u32 v252, v180, 4, v252
	v_add_u32_e32 v252, 0x4000, v252
	v_mul_u32_u24_e32 v253, 0x220, v179
	v_lshl_add_u32 v253, v180, 4, v253
	v_add_u32_e32 v253, 0xe000, v253
	v_bfe_u32 v218, v115, 2, 2
	s_lshl_b32 s57, s69, 5
	v_and_b32_e32 v203, 3, v115
	v_or_b32_e32 v202, s68, v218
	s_sub_i32 s58, 0xfe0, s57
	v_readlane_b32 s6, v255, 24
	v_add_u32_e32 v126, s58, v202
	v_ashrrev_i32_e32 v127, 31, v126
	v_or_b32_e32 v117, s6, v203
	v_readlane_b32 s6, v255, 25
	v_readlane_b32 s7, v255, 26
	s_movk_i32 s8, 0x60
	v_mul_u32_u24_e32 v2, 3, v117
	v_lshl_add_u64 v[118:119], v[126:127], 0, s[6:7]
	v_readlane_b32 s6, v255, 27
	v_readlane_b32 s7, v255, 28
	v_lshlrev_b32_e32 v136, 2, v2
	v_ashrrev_i32_e32 v125, 4, v115
	v_mov_b64_e32 v[0:1], s[6:7]
	v_mad_u64_u32 v[0:1], s[6:7], v118, s8, v[0:1]
	v_mad_i32_i24 v1, v119, s8, v1
	v_readlane_b32 s6, v255, 50
	v_lshl_add_u64 v[6:7], v[0:1], 0, v[136:137]
	v_add_u32_e32 v10, s63, v115
	v_lshl_or_b32 v136, v117, 19, s6
	v_readlane_b32 s6, v255, 29
	v_readlane_b32 s7, v255, 30
	v_lshlrev_b64 v[2:3], 7, v[126:127]
	v_lshlrev_b32_e32 v4, 3, v125
	v_lshl_add_u64 v[0:1], s[6:7], 0, v[136:137]
	v_readlane_b32 s6, v255, 22
	v_lshl_add_u64 v[0:1], v[0:1], 0, v[2:3]
	v_ashrrev_i32_e32 v5, 31, v4
	v_lshlrev_b64 v[8:9], 6, v[118:119]
	v_readlane_b32 s7, v255, 23
	v_ashrrev_i32_e32 v120, 3, v10
	v_lshl_add_u64 v[0:1], v[4:5], 1, v[0:1]
	v_lshl_add_u64 v[8:9], s[6:7], 0, v[8:9]
	v_ashrrev_i32_e32 v121, 31, v120
	v_lshlrev_b32_e32 v10, 3, v115
	global_load_dwordx4 v[36:39], v[0:1], off
	s_nop 0
	global_load_dwordx4 v[0:3], v[0:1], off offset:64
	s_waitcnt vmcnt(0)
	global_load_dwordx4 v[44:47], v[8:9], off
	global_load_dwordx4 v[32:35], v[8:9], off offset:16
	global_load_dwordx4 v[40:43], v[8:9], off offset:32
	global_load_dwordx4 v[28:31], v[8:9], off offset:48
	v_lshlrev_b64 v[8:9], 7, v[120:121]
	v_and_b32_e32 v124, 56, v10
	v_lshl_add_u64 v[8:9], s[64:65], 0, v[8:9]
	v_lshlrev_b32_e32 v136, 1, v124
	v_readlane_b32 s6, v255, 31
	v_lshl_add_u64 v[8:9], v[8:9], 0, v[136:137]
	v_lshlrev_b64 v[122:123], 13, v[120:121]
	v_readlane_b32 s7, v255, 32
	global_load_dwordx4 v[20:23], v[8:9], off
	s_add_i32 s56, s58, s68
	v_lshl_add_u64 v[8:9], s[6:7], 0, v[122:123]
	v_lshl_add_u64 v[128:129], v[8:9], 0, v[136:137]
	global_load_dwordx3 v[112:114], v[6:7], off
	global_load_dwordx4 v[24:27], v[128:129], off
	s_sub_i32 s7, s56, 28
	s_ashr_i32 s7, s7, 8
	s_or_b32 s6, s56, 3
	s_add_i32 s7, s7, 1
	s_cmp_gt_i32 s6, 30
	v_and_b32_e32 v121, 15, v115
	s_cselect_b32 s40, s7, 0
	v_lshlrev_b32_e32 v6, 6, v121
	s_cmp_gt_i32 s40, 0
	s_cselect_b64 s[38:39], -1, 0
	s_cmp_lt_i32 s40, 1
	v_lshlrev_b32_e32 v6, 1, v6
	s_cmp_gt_i32 s40, 1
	s_cselect_b64 s[20:21], -1, 0
	s_cmp_gt_i32 s40, 2
	s_cselect_b64 s[36:37], -1, 0
	s_cmp_gt_i32 s40, 3
	s_cselect_b64 s[18:19], -1, 0
	s_cmp_gt_i32 s40, 4
	s_cselect_b64 s[34:35], -1, 0
	s_cmp_gt_i32 s40, 5
	s_cselect_b64 s[16:17], -1, 0
	s_cmp_gt_i32 s40, 6
	s_cselect_b64 s[30:31], -1, 0
	s_cmp_gt_i32 s40, 7
	s_cselect_b64 s[14:15], -1, 0
	s_cmp_gt_i32 s40, 8
	s_cselect_b64 s[28:29], -1, 0
	s_cmp_gt_i32 s40, 9
	s_cselect_b64 s[12:13], -1, 0
	s_cmp_gt_i32 s40, 10
	s_cselect_b64 s[26:27], -1, 0
	s_cmp_gt_i32 s40, 11
	s_cselect_b64 s[10:11], -1, 0
	s_cmp_gt_i32 s40, 12
	s_cselect_b64 s[24:25], -1, 0
	s_cmp_gt_i32 s40, 13
	s_cselect_b64 s[8:9], -1, 0
	s_cmp_gt_i32 s40, 14
	s_cselect_b64 s[22:23], -1, 0
	s_cmp_gt_i32 s40, 15
	s_cselect_b64 s[6:7], -1, 0
	v_mov_b32_e32 v7, v137
	v_lshl_add_u64 v[138:139], s[42:43], 0, v[6:7]
	v_lshl_add_u64 v[138:139], v[4:5], 1, v[138:139]
	v_add_co_u32_e32 v138, vcc, 0x1000, v138
	s_nop 1
	v_addc_co_u32_e32 v139, vcc, 0, v139, vcc
	s_waitcnt vmcnt(0)
	ds_write_b128 v177, v[140:143]
	ds_write_b128 v177, v[144:147] offset:10240
	ds_write_b128 v177, v[148:151] offset:20480
	ds_write_b128 v177, v[152:155] offset:30720
	ds_write_b128 v178, v[156:159]
	ds_write_b128 v178, v[160:163] offset:8704
	ds_write_b128 v178, v[164:167] offset:17408
	ds_write_b128 v178, v[168:171] offset:26112
	s_waitcnt lgkmcnt(0)
	s_barrier
	s_cmp_lt_i32 s40, 1
	s_cbranch_scc1 .Lcq_issued
	ds_read_b128 v[48:51], v252
	ds_read_b128 v[140:143], v252 offset:64
	s_cmp_lt_i32 s40, 2
	s_cbranch_scc1 .Lcq_issued
	ds_read_b128 v[52:55], v252 offset:2560
	ds_read_b128 v[144:147], v252 offset:2624
	s_cmp_lt_i32 s40, 3
	s_cbranch_scc1 .Lcq_issued
	ds_read_b128 v[56:59], v252 offset:5120
	ds_read_b128 v[148:151], v252 offset:5184
	s_cmp_lt_i32 s40, 4
	s_cbranch_scc1 .Lcq_issued
	ds_read_b128 v[60:63], v252 offset:7680
	ds_read_b128 v[152:155], v252 offset:7744
	v_add_co_u32_e32 v138, vcc, 0x2000, v138
	s_nop 1
	v_addc_co_u32_e32 v139, vcc, 0, v139, vcc
	s_cmp_lt_i32 s40, 5
	s_cbranch_scc1 .Lcq_issued
	ds_read_b128 v[64:67], v252 offset:10240
	ds_read_b128 v[156:159], v252 offset:10304
	s_cmp_lt_i32 s40, 6
	s_cbranch_scc1 .Lcq_issued
	ds_read_b128 v[68:71], v252 offset:12800
	ds_read_b128 v[160:163], v252 offset:12864
	s_cmp_lt_i32 s40, 7
	s_cbranch_scc1 .Lcq_issued
	ds_read_b128 v[72:75], v252 offset:15360
	ds_read_b128 v[164:167], v252 offset:15424
	s_cmp_lt_i32 s40, 8
	s_cbranch_scc1 .Lcq_issued
	ds_read_b128 v[76:79], v252 offset:17920
	ds_read_b128 v[168:171], v252 offset:17984
	v_add_co_u32_e32 v138, vcc, 0x2000, v138
	s_nop 1
	v_addc_co_u32_e32 v139, vcc, 0, v139, vcc
	s_cmp_lt_i32 s40, 9
	s_cbranch_scc1 .Lcq_issued
	ds_read_b128 v[80:83], v252 offset:20480
	ds_read_b128 v[172:175], v252 offset:20544
	s_cmp_lt_i32 s40, 10
	s_cbranch_scc1 .Lcq_issued
	ds_read_b128 v[84:87], v252 offset:23040
	ds_read_b128 v[176:179], v252 offset:23104
	s_cmp_lt_i32 s40, 11
	s_cbranch_scc1 .Lcq_issued
	ds_read_b128 v[88:91], v252 offset:25600
	ds_read_b128 v[180:183], v252 offset:25664
	s_cmp_lt_i32 s40, 12
	s_cbranch_scc1 .Lcq_issued
	ds_read_b128 v[92:95], v252 offset:28160
	ds_read_b128 v[184:187], v252 offset:28224
	v_add_co_u32_e32 v138, vcc, 0x2000, v138
	s_nop 1
	v_addc_co_u32_e32 v139, vcc, 0, v139, vcc
	s_cmp_lt_i32 s40, 13
	s_cbranch_scc1 .Lcq_issued
	ds_read_b128 v[96:99], v252 offset:30720
	ds_read_b128 v[188:191], v252 offset:30784
	s_cmp_lt_i32 s40, 14
	s_cbranch_scc1 .Lcq_issued
	ds_read_b128 v[100:103], v252 offset:33280
	ds_read_b128 v[192:195], v252 offset:33344
	s_cmp_lt_i32 s40, 15
	s_cbranch_scc1 .Lcq_issued
	ds_read_b128 v[104:107], v252 offset:35840
	ds_read_b128 v[196:199], v252 offset:35904
	s_cmp_lt_i32 s40, 16
	s_cbranch_scc1 .Lcq_issued
	ds_read_b128 v[108:111], v252 offset:38400
	ds_read_b128 v[204:207], v252 offset:38464

.Lcq_done:
.LBB0_447:
	s_nop 6
	v_subrev_u32_e32 v6, 31, v126
	v_lshrrev_b32_e32 v6, 4, v6
	v_cmp_lt_i32_e32 vcc, 30, v126
	v_lshlrev_b32_e32 v116, 2, v125
	v_mul_f32_e32 v7, 0x3e38aa3b, v48
	v_cndmask_b32_e32 v6, -1, v6, vcc
	v_cmp_le_i32_e32 vcc, v116, v6
	v_mul_f32_e32 v9, 0x3e38aa3b, v49
	v_mul_f32_e32 v10, 0x3e38aa3b, v50
	v_cndmask_b32_e32 v7, v241, v7, vcc
	v_max_f32_e32 v8, 0xf149f2ca, v7
	v_cmp_lt_i32_e32 vcc, v116, v6
	v_cndmask_b32_e64 v8, v241, v8, s[38:39]
	v_mul_f32_e32 v11, 0x3e38aa3b, v53
	v_cndmask_b32_e32 v16, v241, v9, vcc
	v_or_b32_e32 v9, 2, v116
	v_max_f32_e32 v8, v8, v16
	v_cmp_le_i32_e32 vcc, v9, v6
	v_cndmask_b32_e64 v8, v241, v8, s[38:39]
	v_or_b32_e32 v9, 3, v116
	v_cndmask_b32_e32 v18, v241, v10, vcc
	v_max_f32_e32 v8, v8, v18
	v_mul_f32_e32 v10, 0x3e38aa3b, v51
	v_cmp_le_i32_e32 vcc, v9, v6
	v_cndmask_b32_e64 v8, v241, v8, s[38:39]
	v_add_u32_e32 v9, 16, v116
	v_cndmask_b32_e32 v131, v241, v10, vcc
	v_max_f32_e32 v8, v8, v131
	v_mul_f32_e32 v10, 0x3e38aa3b, v52
	v_cmp_le_i32_e32 vcc, v9, v6
	v_cndmask_b32_e64 v8, v241, v8, s[38:39]
	v_mul_f32_e32 v133, 0x3e38aa3b, v110
	v_cndmask_b32_e32 v140, v241, v10, vcc
	v_add_u32_e32 v10, 17, v116
	v_max_f32_e32 v9, v8, v140
	v_cmp_le_i32_e32 vcc, v10, v6
	v_cndmask_b32_e64 v9, v8, v9, s[20:21]
	v_add_u32_e32 v10, 18, v116
	v_cndmask_b32_e32 v141, v241, v11, vcc
	v_max_f32_e32 v9, v9, v141
	v_mul_f32_e32 v11, 0x3e38aa3b, v54
	v_cmp_le_i32_e32 vcc, v10, v6
	v_cndmask_b32_e64 v9, v8, v9, s[20:21]
	v_add_u32_e32 v10, 19, v116
	v_cndmask_b32_e32 v142, v241, v11, vcc
	v_max_f32_e32 v9, v9, v142
	v_mul_f32_e32 v11, 0x3e38aa3b, v55
	v_cmp_le_i32_e32 vcc, v10, v6
	v_cndmask_b32_e64 v9, v8, v9, s[20:21]
	v_mul_f32_e32 v10, 0x3e38aa3b, v56
	v_cndmask_b32_e32 v143, v241, v11, vcc
	v_max_f32_e32 v9, v9, v143
	v_cndmask_b32_e64 v8, v8, v9, s[20:21]
	v_add_u32_e32 v9, 32, v116
	v_cmp_le_i32_e32 vcc, v9, v6
	v_mul_f32_e32 v11, 0x3e38aa3b, v57
	v_mul_f32_e32 v134, 0x3e38aa3b, v111
	v_cndmask_b32_e32 v144, v241, v10, vcc
	v_add_u32_e32 v10, 33, v116
	v_max_f32_e32 v9, v8, v144
	v_cmp_le_i32_e32 vcc, v10, v6
	v_cndmask_b32_e64 v9, v8, v9, s[36:37]
	v_add_u32_e32 v10, 34, v116
	v_cndmask_b32_e32 v145, v241, v11, vcc
	v_max_f32_e32 v9, v9, v145
	v_mul_f32_e32 v11, 0x3e38aa3b, v58
	v_cmp_le_i32_e32 vcc, v10, v6
	v_cndmask_b32_e64 v9, v8, v9, s[36:37]
	v_add_u32_e32 v10, 35, v116
	v_cndmask_b32_e32 v146, v241, v11, vcc
	v_max_f32_e32 v9, v9, v146
	v_mul_f32_e32 v11, 0x3e38aa3b, v59
	v_cmp_le_i32_e32 vcc, v10, v6
	v_cndmask_b32_e64 v9, v8, v9, s[36:37]
	v_mul_f32_e32 v10, 0x3e38aa3b, v60
	v_cndmask_b32_e32 v152, v241, v11, vcc
	v_max_f32_e32 v9, v9, v152
	v_cndmask_b32_e64 v8, v8, v9, s[36:37]
	v_add_u32_e32 v9, 48, v116
	v_cmp_le_i32_e32 vcc, v9, v6
	v_mul_f32_e32 v11, 0x3e38aa3b, v61
	v_cndmask_b32_e64 v16, v49, v16, s[38:39]
	v_cndmask_b32_e32 v153, v241, v10, vcc
	v_add_u32_e32 v10, 49, v116
	v_max_f32_e32 v9, v8, v153
	v_cmp_le_i32_e32 vcc, v10, v6
	v_cndmask_b32_e64 v9, v8, v9, s[18:19]
	v_add_u32_e32 v10, 50, v116
	v_cndmask_b32_e32 v154, v241, v11, vcc
	v_max_f32_e32 v9, v9, v154
	v_mul_f32_e32 v11, 0x3e38aa3b, v62
	v_cmp_le_i32_e32 vcc, v10, v6
	v_cndmask_b32_e64 v9, v8, v9, s[18:19]
	v_add_u32_e32 v10, 51, v116
	v_cndmask_b32_e32 v155, v241, v11, vcc
	v_max_f32_e32 v9, v9, v155
	v_mul_f32_e32 v11, 0x3e38aa3b, v63
	v_cmp_le_i32_e32 vcc, v10, v6
	v_cndmask_b32_e64 v9, v8, v9, s[18:19]
	v_mul_f32_e32 v10, 0x3e38aa3b, v64
	v_cndmask_b32_e32 v156, v241, v11, vcc
	v_max_f32_e32 v9, v9, v156
	v_cndmask_b32_e64 v8, v8, v9, s[18:19]
	v_add_u32_e32 v9, 64, v116
	v_cmp_le_i32_e32 vcc, v9, v6
	v_mul_f32_e32 v11, 0x3e38aa3b, v65
	v_cndmask_b32_e64 v18, v50, v18, s[38:39]
	v_cndmask_b32_e32 v157, v241, v10, vcc
	v_max_f32_e32 v9, v8, v157
	v_add_u32_e32 v10, 0x41, v116
	v_cndmask_b32_e64 v9, v8, v9, s[34:35]
	v_cmp_le_i32_e32 vcc, v10, v6
	v_max_f32_e32 v9, v9, v9
	v_add_u32_e32 v10, 0x42, v116
	v_cndmask_b32_e32 v158, v241, v11, vcc
	v_max_f32_e32 v9, v9, v158
	v_cndmask_b32_e64 v9, v8, v9, s[34:35]
	v_mul_f32_e32 v11, 0x3e38aa3b, v66
	v_cmp_le_i32_e32 vcc, v10, v6
	v_max_f32_e32 v9, v9, v9
	v_add_u32_e32 v10, 0x43, v116
	v_cndmask_b32_e32 v159, v241, v11, vcc
	v_max_f32_e32 v9, v9, v159
	v_cndmask_b32_e64 v9, v8, v9, s[34:35]
	v_mul_f32_e32 v11, 0x3e38aa3b, v67
	v_cmp_le_i32_e32 vcc, v10, v6
	v_max_f32_e32 v9, v9, v9
	v_mul_f32_e32 v10, 0x3e38aa3b, v68
	v_cndmask_b32_e32 v160, v241, v11, vcc
	v_max_f32_e32 v9, v9, v160
	v_cndmask_b32_e64 v8, v8, v9, s[34:35]
	v_add_u32_e32 v9, 0x50, v116
	v_cmp_le_i32_e32 vcc, v9, v6
	v_max_f32_e32 v9, v8, v8
	v_mul_f32_e32 v11, 0x3e38aa3b, v69
	v_cndmask_b32_e32 v161, v241, v10, vcc
	v_max_f32_e32 v9, v9, v161
	v_add_u32_e32 v10, 0x51, v116
	v_cndmask_b32_e64 v9, v8, v9, s[16:17]
	v_cmp_le_i32_e32 vcc, v10, v6
	v_max_f32_e32 v9, v9, v9
	v_add_u32_e32 v10, 0x52, v116
	v_cndmask_b32_e32 v162, v241, v11, vcc
	v_max_f32_e32 v9, v9, v162
	v_cndmask_b32_e64 v9, v8, v9, s[16:17]
	v_mul_f32_e32 v11, 0x3e38aa3b, v70
	v_cmp_le_i32_e32 vcc, v10, v6
	v_max_f32_e32 v9, v9, v9
	v_add_u32_e32 v10, 0x53, v116
	v_cndmask_b32_e32 v163, v241, v11, vcc
	v_max_f32_e32 v9, v9, v163
	v_cndmask_b32_e64 v9, v8, v9, s[16:17]
	v_mul_f32_e32 v11, 0x3e38aa3b, v71
	v_cmp_le_i32_e32 vcc, v10, v6
	v_max_f32_e32 v9, v9, v9
	v_mul_f32_e32 v10, 0x3e38aa3b, v72
	v_cndmask_b32_e32 v164, v241, v11, vcc
	v_max_f32_e32 v9, v9, v164
	v_cndmask_b32_e64 v8, v8, v9, s[16:17]
	v_add_u32_e32 v9, 0x60, v116
	v_cmp_le_i32_e32 vcc, v9, v6
	v_max_f32_e32 v9, v8, v8
	v_mul_f32_e32 v11, 0x3e38aa3b, v73
	v_cndmask_b32_e32 v165, v241, v10, vcc
	v_max_f32_e32 v9, v9, v165
	v_add_u32_e32 v10, 0x61, v116
	v_cndmask_b32_e64 v9, v8, v9, s[30:31]
	v_cmp_le_i32_e32 vcc, v10, v6
	v_max_f32_e32 v9, v9, v9
	v_add_u32_e32 v10, 0x62, v116
	v_cndmask_b32_e32 v166, v241, v11, vcc
	v_max_f32_e32 v9, v9, v166
	v_cndmask_b32_e64 v9, v8, v9, s[30:31]
	v_mul_f32_e32 v11, 0x3e38aa3b, v74
	v_cmp_le_i32_e32 vcc, v10, v6
	v_max_f32_e32 v9, v9, v9
	v_add_u32_e32 v10, 0x63, v116
	v_cndmask_b32_e32 v167, v241, v11, vcc
	v_max_f32_e32 v9, v9, v167
	v_cndmask_b32_e64 v9, v8, v9, s[30:31]
	v_mul_f32_e32 v11, 0x3e38aa3b, v75
	v_cmp_le_i32_e32 vcc, v10, v6
	v_max_f32_e32 v9, v9, v9
	v_mul_f32_e32 v10, 0x3e38aa3b, v76
	v_cndmask_b32_e32 v168, v241, v11, vcc
	v_max_f32_e32 v9, v9, v168
	v_cndmask_b32_e64 v8, v8, v9, s[30:31]
	v_add_u32_e32 v9, 0x70, v116
	v_cmp_le_i32_e32 vcc, v9, v6
	v_max_f32_e32 v9, v8, v8
	v_mul_f32_e32 v11, 0x3e38aa3b, v77
	v_cndmask_b32_e32 v172, v241, v10, vcc
	v_max_f32_e32 v9, v9, v172
	v_add_u32_e32 v10, 0x71, v116
	v_cndmask_b32_e64 v9, v8, v9, s[14:15]
	v_cmp_le_i32_e32 vcc, v10, v6
	v_max_f32_e32 v9, v9, v9
	v_add_u32_e32 v10, 0x72, v116
	v_cndmask_b32_e32 v173, v241, v11, vcc
	v_max_f32_e32 v9, v9, v173
	v_cndmask_b32_e64 v9, v8, v9, s[14:15]
	v_mul_f32_e32 v11, 0x3e38aa3b, v78
	v_cmp_le_i32_e32 vcc, v10, v6
	v_max_f32_e32 v9, v9, v9
	v_add_u32_e32 v10, 0x73, v116
	v_cndmask_b32_e32 v174, v241, v11, vcc
	v_max_f32_e32 v9, v9, v174
	v_cndmask_b32_e64 v9, v8, v9, s[14:15]
	v_mul_f32_e32 v11, 0x3e38aa3b, v79
	v_cmp_le_i32_e32 vcc, v10, v6
	v_max_f32_e32 v9, v9, v9
	v_mul_f32_e32 v10, 0x3e38aa3b, v80
	v_cndmask_b32_e32 v175, v241, v11, vcc
	v_max_f32_e32 v9, v9, v175
	v_cndmask_b32_e64 v8, v8, v9, s[14:15]
	v_add_u32_e32 v9, 0x80, v116
	v_cmp_le_i32_e32 vcc, v9, v6
	v_max_f32_e32 v9, v8, v8
	v_mul_f32_e32 v11, 0x3e38aa3b, v81
	v_cndmask_b32_e32 v176, v241, v10, vcc
	v_max_f32_e32 v9, v9, v176
	v_add_u32_e32 v10, 0x81, v116
	v_cndmask_b32_e64 v9, v8, v9, s[28:29]
	v_cmp_le_i32_e32 vcc, v10, v6
	v_max_f32_e32 v9, v9, v9
	v_add_u32_e32 v10, 0x82, v116
	v_cndmask_b32_e32 v177, v241, v11, vcc
	v_max_f32_e32 v9, v9, v177
	v_cndmask_b32_e64 v9, v8, v9, s[28:29]
	v_mul_f32_e32 v11, 0x3e38aa3b, v82
	v_cmp_le_i32_e32 vcc, v10, v6
	v_max_f32_e32 v9, v9, v9
	v_add_u32_e32 v10, 0x83, v116
	v_cndmask_b32_e32 v178, v241, v11, vcc
	v_max_f32_e32 v9, v9, v178
	v_cndmask_b32_e64 v9, v8, v9, s[28:29]
	v_mul_f32_e32 v11, 0x3e38aa3b, v83
	v_cmp_le_i32_e32 vcc, v10, v6
	v_max_f32_e32 v9, v9, v9
	v_mul_f32_e32 v10, 0x3e38aa3b, v84
	v_cndmask_b32_e32 v179, v241, v11, vcc
	v_max_f32_e32 v9, v9, v179
	v_cndmask_b32_e64 v8, v8, v9, s[28:29]
	v_add_u32_e32 v9, 0x90, v116
	v_cmp_le_i32_e32 vcc, v9, v6
	v_max_f32_e32 v9, v8, v8
	v_mul_f32_e32 v11, 0x3e38aa3b, v85
	v_cndmask_b32_e32 v180, v241, v10, vcc
	v_max_f32_e32 v9, v9, v180
	v_add_u32_e32 v10, 0x91, v116
	v_cndmask_b32_e64 v9, v8, v9, s[12:13]
	v_cmp_le_i32_e32 vcc, v10, v6
	v_max_f32_e32 v9, v9, v9
	v_add_u32_e32 v10, 0x92, v116
	v_cndmask_b32_e32 v181, v241, v11, vcc
	v_max_f32_e32 v9, v9, v181
	v_cndmask_b32_e64 v9, v8, v9, s[12:13]
	v_mul_f32_e32 v11, 0x3e38aa3b, v86
	v_cmp_le_i32_e32 vcc, v10, v6
	v_max_f32_e32 v9, v9, v9
	v_add_u32_e32 v10, 0x93, v116
	v_cndmask_b32_e32 v182, v241, v11, vcc
	v_max_f32_e32 v9, v9, v182
	v_cndmask_b32_e64 v9, v8, v9, s[12:13]
	v_mul_f32_e32 v11, 0x3e38aa3b, v87
	v_cmp_le_i32_e32 vcc, v10, v6
	v_max_f32_e32 v9, v9, v9
	v_mul_f32_e32 v10, 0x3e38aa3b, v88
	v_cndmask_b32_e32 v183, v241, v11, vcc
	v_max_f32_e32 v9, v9, v183
	v_cndmask_b32_e64 v8, v8, v9, s[12:13]
	v_add_u32_e32 v9, 0xa0, v116
	v_cmp_le_i32_e32 vcc, v9, v6
	v_max_f32_e32 v9, v8, v8
	v_mul_f32_e32 v11, 0x3e38aa3b, v89
	v_cndmask_b32_e32 v184, v241, v10, vcc
	v_max_f32_e32 v9, v9, v184
	v_add_u32_e32 v10, 0xa1, v116
	v_cndmask_b32_e64 v9, v8, v9, s[26:27]
	v_cmp_le_i32_e32 vcc, v10, v6
	v_max_f32_e32 v9, v9, v9
	v_add_u32_e32 v10, 0xa2, v116
	v_cndmask_b32_e32 v188, v241, v11, vcc
	v_max_f32_e32 v9, v9, v188
	v_cndmask_b32_e64 v9, v8, v9, s[26:27]
	v_mul_f32_e32 v11, 0x3e38aa3b, v90
	v_cmp_le_i32_e32 vcc, v10, v6
	v_max_f32_e32 v9, v9, v9
	v_add_u32_e32 v10, 0xa3, v116
	v_cndmask_b32_e32 v189, v241, v11, vcc
	v_max_f32_e32 v9, v9, v189
	v_cndmask_b32_e64 v9, v8, v9, s[26:27]
	v_mul_f32_e32 v11, 0x3e38aa3b, v91
	v_cmp_le_i32_e32 vcc, v10, v6
	v_max_f32_e32 v9, v9, v9
	v_mul_f32_e32 v10, 0x3e38aa3b, v92
	v_cndmask_b32_e32 v190, v241, v11, vcc
	v_max_f32_e32 v9, v9, v190
	v_cndmask_b32_e64 v8, v8, v9, s[26:27]
	v_add_u32_e32 v9, 0xb0, v116
	v_cmp_le_i32_e32 vcc, v9, v6
	v_max_f32_e32 v9, v8, v8
	v_mul_f32_e32 v11, 0x3e38aa3b, v93
	v_cndmask_b32_e32 v150, v241, v10, vcc
	v_max_f32_e32 v9, v9, v150
	v_add_u32_e32 v10, 0xb1, v116
	v_cndmask_b32_e64 v9, v8, v9, s[10:11]
	v_cmp_le_i32_e32 vcc, v10, v6
	v_max_f32_e32 v9, v9, v9
	v_add_u32_e32 v10, 0xb2, v116
	v_cndmask_b32_e32 v151, v241, v11, vcc
	v_max_f32_e32 v9, v9, v151
	v_cndmask_b32_e64 v9, v8, v9, s[10:11]
	v_mul_f32_e32 v11, 0x3e38aa3b, v94
	v_cmp_le_i32_e32 vcc, v10, v6
	v_max_f32_e32 v9, v9, v9
	v_add_u32_e32 v10, 0xb3, v116
	v_cndmask_b32_e32 v148, v241, v11, vcc
	v_max_f32_e32 v9, v9, v148
	v_cndmask_b32_e64 v9, v8, v9, s[10:11]
	v_mul_f32_e32 v11, 0x3e38aa3b, v95
	v_cmp_le_i32_e32 vcc, v10, v6
	v_max_f32_e32 v9, v9, v9
	v_mul_f32_e32 v10, 0x3e38aa3b, v96
	v_cndmask_b32_e32 v149, v241, v11, vcc
	v_max_f32_e32 v9, v9, v149
	v_cndmask_b32_e64 v8, v8, v9, s[10:11]
	v_add_u32_e32 v9, 0xc0, v116
	v_cmp_le_i32_e32 vcc, v9, v6
	v_max_f32_e32 v9, v8, v8
	v_mul_f32_e32 v11, 0x3e38aa3b, v97
	v_cndmask_b32_e32 v139, v241, v10, vcc
	v_max_f32_e32 v9, v9, v139
	v_add_u32_e32 v10, 0xc1, v116
	v_cndmask_b32_e64 v9, v8, v9, s[24:25]
	v_cmp_le_i32_e32 vcc, v10, v6
	v_max_f32_e32 v9, v9, v9
	v_add_u32_e32 v10, 0xc2, v116
	v_cndmask_b32_e32 v147, v241, v11, vcc
	v_max_f32_e32 v9, v9, v147
	v_cndmask_b32_e64 v9, v8, v9, s[24:25]
	v_mul_f32_e32 v11, 0x3e38aa3b, v98
	v_cmp_le_i32_e32 vcc, v10, v6
	v_max_f32_e32 v9, v9, v9
	v_add_u32_e32 v10, 0xc3, v116
	v_cndmask_b32_e32 v135, v241, v11, vcc
	v_max_f32_e32 v9, v9, v135
	v_cndmask_b32_e64 v9, v8, v9, s[24:25]
	v_mul_f32_e32 v11, 0x3e38aa3b, v99
	v_cmp_le_i32_e32 vcc, v10, v6
	v_max_f32_e32 v9, v9, v9
	v_mul_f32_e32 v10, 0x3e38aa3b, v100
	v_cndmask_b32_e32 v138, v241, v11, vcc
	v_max_f32_e32 v9, v9, v138
	v_cndmask_b32_e64 v8, v8, v9, s[24:25]
	v_add_u32_e32 v9, 0xd0, v116
	v_cmp_le_i32_e32 vcc, v9, v6
	v_max_f32_e32 v9, v8, v8
	v_mul_f32_e32 v11, 0x3e38aa3b, v101
	v_cndmask_b32_e32 v130, v241, v10, vcc
	v_max_f32_e32 v9, v9, v130
	v_add_u32_e32 v10, 0xd1, v116
	v_cndmask_b32_e64 v9, v8, v9, s[8:9]
	v_cmp_le_i32_e32 vcc, v10, v6
	v_max_f32_e32 v9, v9, v9
	v_add_u32_e32 v10, 0xd2, v116
	v_cndmask_b32_e32 v132, v241, v11, vcc
	v_max_f32_e32 v9, v9, v132
	v_cndmask_b32_e64 v9, v8, v9, s[8:9]
	v_mul_f32_e32 v11, 0x3e38aa3b, v102
	v_cmp_le_i32_e32 vcc, v10, v6
	v_max_f32_e32 v9, v9, v9
	v_add_u32_e32 v10, 0xd3, v116
	v_cndmask_b32_e32 v17, v241, v11, vcc
	v_max_f32_e32 v9, v9, v17
	v_cndmask_b32_e64 v9, v8, v9, s[8:9]
	v_mul_f32_e32 v11, 0x3e38aa3b, v103
	v_cmp_le_i32_e32 vcc, v10, v6
	v_max_f32_e32 v9, v9, v9
	v_mul_f32_e32 v10, 0x3e38aa3b, v104
	v_cndmask_b32_e32 v19, v241, v11, vcc
	v_max_f32_e32 v9, v9, v19
	v_cndmask_b32_e64 v8, v8, v9, s[8:9]
	v_add_u32_e32 v9, 0xe0, v116
	v_cmp_le_i32_e32 vcc, v9, v6
	v_max_f32_e32 v9, v8, v8
	v_mul_f32_e32 v11, 0x3e38aa3b, v105
	v_cndmask_b32_e32 v14, v241, v10, vcc
	v_max_f32_e32 v9, v9, v14
	v_add_u32_e32 v10, 0xe1, v116
	v_cndmask_b32_e64 v9, v8, v9, s[22:23]
	v_cmp_le_i32_e32 vcc, v10, v6
	v_max_f32_e32 v9, v9, v9
	v_add_u32_e32 v10, 0xe2, v116
	v_cndmask_b32_e32 v15, v241, v11, vcc
	v_max_f32_e32 v9, v9, v15
	v_cndmask_b32_e64 v9, v8, v9, s[22:23]
	v_mul_f32_e32 v11, 0x3e38aa3b, v106
	v_cmp_le_i32_e32 vcc, v10, v6
	v_max_f32_e32 v9, v9, v9
	v_add_u32_e32 v10, 0xe3, v116
	v_cndmask_b32_e32 v12, v241, v11, vcc
	v_max_f32_e32 v9, v9, v12
	v_cndmask_b32_e64 v9, v8, v9, s[22:23]
	v_mul_f32_e32 v11, 0x3e38aa3b, v107
	v_cmp_le_i32_e32 vcc, v10, v6
	v_max_f32_e32 v9, v9, v9
	v_cndmask_b32_e64 v131, v51, v131, s[38:39]
	v_cndmask_b32_e32 v13, v241, v11, vcc
	v_max_f32_e32 v9, v9, v13
	v_cndmask_b32_e64 v127, v8, v9, s[22:23]
	v_add_u32_e32 v8, 0xf0, v116
	v_mul_f32_e32 v9, 0x3e38aa3b, v108
	v_cmp_le_i32_e32 vcc, v8, v6
	v_max_f32_e32 v8, v127, v127
	v_mul_f32_e32 v11, 0x3e38aa3b, v109
	v_cndmask_b32_e32 v10, v241, v9, vcc
	v_max_f32_e32 v8, v8, v10
	v_add_u32_e32 v9, 0xf1, v116
	v_cndmask_b32_e64 v8, v127, v8, s[6:7]
	v_cmp_le_i32_e32 vcc, v9, v6
	v_max_f32_e32 v8, v8, v8
	v_cndmask_b32_e64 v143, v55, v143, s[20:21]
	v_cndmask_b32_e32 v11, v241, v11, vcc
	v_max_f32_e32 v8, v8, v11
	v_cndmask_b32_e64 v9, v127, v8, s[6:7]
	v_add_u32_e32 v8, 0xf2, v116
	v_cmp_le_i32_e32 vcc, v8, v6
	v_max_f32_e32 v9, v9, v9
	v_cndmask_b32_e64 v150, v92, v150, s[10:11]
	v_cndmask_b32_e32 v8, v241, v133, vcc
	v_max_f32_e32 v9, v9, v8
	v_cndmask_b32_e64 v133, v127, v9, s[6:7]
	v_add_u32_e32 v9, 0xf3, v116
	v_cmp_le_i32_e32 vcc, v9, v6
	v_max_f32_e32 v6, v133, v133
	v_cndmask_b32_e64 v151, v93, v151, s[10:11]
	v_cndmask_b32_e32 v9, v241, v134, vcc
	v_max_f32_e32 v6, v6, v9
	v_cndmask_b32_e64 v6, v127, v6, s[6:7]
	v_lshlrev_b32_e32 v127, 2, v115
	v_xor_b32_e32 v216, 64, v127
	ds_bpermute_b32 v133, v216, v6
	v_max_f32_e32 v6, v6, v6
	v_xor_b32_e32 v217, 0x80, v127
	v_cndmask_b32_e64 v148, v94, v148, s[10:11]
	v_cndmask_b32_e64 v149, v95, v149, s[10:11]
	s_waitcnt lgkmcnt(0)
	v_max_f32_e32 v133, v133, v133
	v_max_f32_e32 v6, v6, v133
	ds_bpermute_b32 v133, v217, v6
	v_cndmask_b32_e64 v139, v96, v139, s[24:25]
	v_cndmask_b32_e64 v147, v97, v147, s[24:25]
	v_cndmask_b32_e64 v135, v98, v135, s[24:25]
	v_cndmask_b32_e64 v138, v99, v138, s[24:25]
	s_waitcnt lgkmcnt(0)
	v_max_f32_e32 v133, v133, v133
	v_max_f32_e32 v133, v6, v133
	v_cndmask_b32_e64 v6, v48, v7, s[38:39]
	v_sub_f32_e32 v7, v6, v133
	v_exp_f32_e32 v7, v7
	v_sub_f32_e32 v134, v16, v133
	v_exp_f32_e32 v134, v134
	v_cmp_lt_f32_e32 vcc, s89, v6
	v_cndmask_b32_e64 v130, v100, v130, s[8:9]
	v_cndmask_b32_e64 v132, v101, v132, s[8:9]
	v_cndmask_b32_e32 v6, 0, v7, vcc
	v_cmp_lt_f32_e32 vcc, s89, v16
	v_add_f32_e32 v169, 0, v6
	v_cndmask_b32_e64 v17, v102, v17, s[8:9]
	v_cndmask_b32_e32 v7, 0, v134, vcc
	v_sub_f32_e32 v134, v18, v133
	v_add_f32_e32 v16, v169, v7
	v_exp_f32_e32 v134, v134
	v_sub_f32_e32 v169, v131, v133
	v_exp_f32_e32 v169, v169
	v_cmp_lt_f32_e32 vcc, s89, v18
	v_cndmask_b32_e64 v19, v103, v19, s[8:9]
	v_cndmask_b32_e64 v14, v104, v14, s[22:23]
	v_cndmask_b32_e32 v18, 0, v134, vcc
	v_cmp_lt_f32_e32 vcc, s89, v131
	v_add_f32_e32 v16, v16, v18
	v_cndmask_b32_e64 v15, v105, v15, s[22:23]
	v_cndmask_b32_e32 v134, 0, v169, vcc
	v_add_f32_e32 v16, v16, v134
	v_cndmask_b32_e64 v169, 0, v16, s[38:39]
	v_cndmask_b32_e64 v16, v52, v140, s[20:21]
	v_sub_f32_e32 v131, v16, v133
	v_cndmask_b32_e64 v140, v53, v141, s[20:21]
	v_exp_f32_e32 v131, v131
	v_sub_f32_e32 v141, v140, v133
	v_exp_f32_e32 v141, v141
	v_cmp_lt_f32_e32 vcc, s89, v16
	v_cndmask_b32_e64 v12, v106, v12, s[22:23]
	v_cndmask_b32_e64 v13, v107, v13, s[22:23]
	v_cndmask_b32_e32 v16, 0, v131, vcc
	v_cmp_lt_f32_e32 vcc, s89, v140
	v_add_f32_e32 v170, v16, v169
	v_cndmask_b32_e64 v10, v108, v10, s[6:7]
	v_cndmask_b32_e32 v131, 0, v141, vcc
	v_cndmask_b32_e64 v141, v54, v142, s[20:21]
	v_sub_f32_e32 v142, v141, v133
	v_add_f32_e32 v140, v131, v170
	v_exp_f32_e32 v142, v142
	v_sub_f32_e32 v170, v143, v133
	v_exp_f32_e32 v170, v170
	v_cmp_lt_f32_e32 vcc, s89, v141
	v_cndmask_b32_e64 v11, v109, v11, s[6:7]
	v_cndmask_b32_e64 v8, v110, v8, s[6:7]
	v_cndmask_b32_e32 v204, 0, v142, vcc
	v_cmp_lt_f32_e32 vcc, s89, v143
	v_add_f32_e32 v140, v204, v140
	v_cndmask_b32_e64 v142, v57, v145, s[36:37]
	v_cndmask_b32_e32 v205, 0, v170, vcc
	v_add_f32_e32 v140, v205, v140
	v_cndmask_b32_e64 v169, v169, v140, s[20:21]
	v_cndmask_b32_e64 v140, v56, v144, s[36:37]
	v_sub_f32_e32 v141, v140, v133
	v_exp_f32_e32 v141, v141
	v_sub_f32_e32 v143, v142, v133
	v_exp_f32_e32 v143, v143
	v_cmp_lt_f32_e32 vcc, s89, v140
	v_cndmask_b32_e64 v145, v59, v152, s[36:37]
	v_cndmask_b32_e64 v9, v111, v9, s[6:7]
	v_cndmask_b32_e32 v140, 0, v141, vcc
	v_cmp_lt_f32_e32 vcc, s89, v142
	v_add_f32_e32 v144, v140, v169
	v_cndmask_b32_e64 v7, v49, v7, s[38:39]
	v_cndmask_b32_e32 v141, 0, v143, vcc
	v_cndmask_b32_e64 v143, v58, v146, s[36:37]
	v_add_f32_e32 v142, v141, v144
	v_sub_f32_e32 v144, v143, v133
	v_exp_f32_e32 v144, v144
	v_sub_f32_e32 v146, v145, v133
	v_exp_f32_e32 v146, v146
	v_cmp_lt_f32_e32 vcc, s89, v143
	v_cndmask_b32_e64 v6, v48, v6, s[38:39]
	s_nop 0
	v_cndmask_b32_e32 v143, 0, v144, vcc
	v_cmp_lt_f32_e32 vcc, s89, v145
	v_add_f32_e32 v144, v143, v142
	s_nop 0
	v_cndmask_b32_e32 v142, 0, v146, vcc
	v_add_f32_e32 v144, v142, v144
	v_cndmask_b32_e64 v152, v169, v144, s[36:37]
	v_cndmask_b32_e64 v144, v60, v153, s[18:19]
	v_sub_f32_e32 v145, v144, v133
	v_cndmask_b32_e64 v146, v61, v154, s[18:19]
	v_exp_f32_e32 v145, v145
	v_sub_f32_e32 v153, v146, v133
	v_exp_f32_e32 v153, v153
	v_cmp_lt_f32_e32 vcc, s89, v144
	s_nop 1
	v_cndmask_b32_e32 v144, 0, v145, vcc
	v_cmp_lt_f32_e32 vcc, s89, v146
	v_add_f32_e32 v154, v144, v152
	v_cndmask_b32_e64 v146, v62, v155, s[18:19]
	v_cndmask_b32_e32 v145, 0, v153, vcc
	v_add_f32_e32 v153, v145, v154
	v_sub_f32_e32 v154, v146, v133
	v_cndmask_b32_e64 v155, v63, v156, s[18:19]
	v_exp_f32_e32 v154, v154
	v_sub_f32_e32 v156, v155, v133
	v_exp_f32_e32 v156, v156
	v_cmp_lt_f32_e32 vcc, s89, v146
	s_nop 1
	v_cndmask_b32_e32 v146, 0, v154, vcc
	v_cmp_lt_f32_e32 vcc, s89, v155
	v_add_f32_e32 v153, v146, v153
	v_cndmask_b32_e64 v155, v65, v158, s[34:35]
	v_cndmask_b32_e32 v171, 0, v156, vcc
	v_add_f32_e32 v153, v171, v153
	v_cndmask_b32_e64 v152, v152, v153, s[18:19]
	v_cndmask_b32_e64 v153, v64, v157, s[34:35]
	v_sub_f32_e32 v154, v153, v133
	v_exp_f32_e32 v154, v154
	v_sub_f32_e32 v156, v155, v133
	v_cmp_lt_f32_e32 vcc, s89, v153
	v_exp_f32_e32 v157, v156
	v_cndmask_b32_e64 v158, v67, v160, s[34:35]
	v_cndmask_b32_e32 v156, 0, v154, vcc
	v_cndmask_b32_e64 v154, v66, v159, s[34:35]
	v_cmp_lt_f32_e32 vcc, s89, v155
	v_sub_f32_e32 v155, v154, v133
	v_exp_f32_e32 v155, v155
	v_sub_f32_e32 v159, v158, v133
	v_exp_f32_e32 v160, v159
	v_add_f32_e32 v153, v156, v152
	v_cndmask_b32_e32 v157, 0, v157, vcc
	v_cmp_lt_f32_e32 vcc, s89, v154
	v_add_f32_e32 v153, v157, v153
	s_nop 0
	v_cndmask_b32_e32 v159, 0, v155, vcc
	v_cmp_lt_f32_e32 vcc, s89, v158
	v_add_f32_e32 v153, v159, v153
	v_cndmask_b32_e64 v155, v69, v162, s[16:17]
	v_cndmask_b32_e32 v158, 0, v160, vcc
	v_add_f32_e32 v153, v158, v153
	v_cndmask_b32_e64 v152, v152, v153, s[34:35]
	v_cndmask_b32_e64 v153, v68, v161, s[16:17]
	v_sub_f32_e32 v154, v153, v133
	v_exp_f32_e32 v154, v154
	v_sub_f32_e32 v160, v155, v133
	v_cmp_lt_f32_e32 vcc, s89, v153
	v_exp_f32_e32 v161, v160
	v_cndmask_b32_e64 v162, v71, v164, s[16:17]
	v_cndmask_b32_e32 v160, 0, v154, vcc
	v_cndmask_b32_e64 v154, v70, v163, s[16:17]
	v_cmp_lt_f32_e32 vcc, s89, v155
	v_sub_f32_e32 v155, v154, v133
	v_exp_f32_e32 v155, v155
	v_sub_f32_e32 v163, v162, v133
	v_exp_f32_e32 v163, v163
	v_add_f32_e32 v153, v160, v152
	v_cndmask_b32_e32 v161, 0, v161, vcc
	v_cmp_lt_f32_e32 vcc, s89, v154
	v_add_f32_e32 v153, v161, v153
	v_cndmask_b32_e64 v164, v75, v168, s[30:31]
	v_cndmask_b32_e32 v170, 0, v155, vcc
	v_cmp_lt_f32_e32 vcc, s89, v162
	v_add_f32_e32 v153, v170, v153
	v_cndmask_b32_e64 v155, v73, v166, s[30:31]
	v_cndmask_b32_e32 v169, 0, v163, vcc
	v_add_f32_e32 v153, v169, v153
	v_cndmask_b32_e64 v152, v152, v153, s[16:17]
	v_cndmask_b32_e64 v153, v72, v165, s[30:31]
	v_sub_f32_e32 v154, v153, v133
	v_exp_f32_e32 v154, v154
	v_sub_f32_e32 v162, v155, v133
	v_cmp_lt_f32_e32 vcc, s89, v153
	v_exp_f32_e32 v163, v162
	v_sub_f32_e32 v165, v164, v133
	v_cndmask_b32_e32 v162, 0, v154, vcc
	v_cndmask_b32_e64 v154, v74, v167, s[30:31]
	v_cmp_lt_f32_e32 vcc, s89, v155
	v_sub_f32_e32 v155, v154, v133
	v_exp_f32_e32 v155, v155
	v_exp_f32_e32 v166, v165
	v_add_f32_e32 v153, v162, v152
	v_cndmask_b32_e32 v163, 0, v163, vcc
	v_cmp_lt_f32_e32 vcc, s89, v154
	v_add_f32_e32 v153, v163, v153
	s_nop 0
	v_cndmask_b32_e32 v165, 0, v155, vcc
	v_cmp_lt_f32_e32 vcc, s89, v164
	v_add_f32_e32 v153, v165, v153
	v_cndmask_b32_e64 v155, v77, v173, s[14:15]
	v_cndmask_b32_e32 v164, 0, v166, vcc
	v_add_f32_e32 v153, v164, v153
	v_cndmask_b32_e64 v152, v152, v153, s[30:31]
	v_cndmask_b32_e64 v153, v76, v172, s[14:15]
	v_sub_f32_e32 v154, v153, v133
	v_exp_f32_e32 v154, v154
	v_sub_f32_e32 v166, v155, v133
	v_cmp_lt_f32_e32 vcc, s89, v153
	v_exp_f32_e32 v167, v166
	v_cndmask_b32_e64 v172, v79, v175, s[14:15]
	v_cndmask_b32_e32 v166, 0, v154, vcc
	v_cndmask_b32_e64 v154, v78, v174, s[14:15]
	v_cmp_lt_f32_e32 vcc, s89, v155
	v_sub_f32_e32 v155, v154, v133
	v_exp_f32_e32 v155, v155
	v_sub_f32_e32 v168, v172, v133
	v_exp_f32_e32 v173, v168
	v_add_f32_e32 v153, v166, v152
	v_cndmask_b32_e32 v167, 0, v167, vcc
	v_cmp_lt_f32_e32 vcc, s89, v154
	v_add_f32_e32 v153, v167, v153
	v_cndmask_b32_e64 v174, v83, v179, s[28:29]
	v_cndmask_b32_e32 v168, 0, v155, vcc
	v_cmp_lt_f32_e32 vcc, s89, v172
	v_add_f32_e32 v153, v168, v153
	v_cndmask_b32_e64 v155, v81, v177, s[28:29]
	v_cndmask_b32_e32 v187, 0, v173, vcc
	v_add_f32_e32 v153, v187, v153
	v_cndmask_b32_e64 v152, v152, v153, s[14:15]
	v_cndmask_b32_e64 v153, v80, v176, s[28:29]
	v_sub_f32_e32 v154, v153, v133
	v_exp_f32_e32 v154, v154
	v_sub_f32_e32 v172, v155, v133
	v_cmp_lt_f32_e32 vcc, s89, v153
	v_exp_f32_e32 v173, v172
	v_sub_f32_e32 v175, v174, v133
	v_cndmask_b32_e32 v172, 0, v154, vcc
	v_cndmask_b32_e64 v154, v82, v178, s[28:29]
	v_cmp_lt_f32_e32 vcc, s89, v155
	v_sub_f32_e32 v155, v154, v133
	v_exp_f32_e32 v155, v155
	v_exp_f32_e32 v176, v175
	v_add_f32_e32 v153, v172, v152
	v_cndmask_b32_e32 v173, 0, v173, vcc
	v_cmp_lt_f32_e32 vcc, s89, v154
	v_add_f32_e32 v153, v173, v153
	v_cndmask_b32_e64 v178, v87, v183, s[12:13]
	v_cndmask_b32_e32 v175, 0, v155, vcc
	v_cmp_lt_f32_e32 vcc, s89, v174
	v_add_f32_e32 v153, v175, v153
	v_cndmask_b32_e64 v155, v85, v181, s[12:13]
	v_cndmask_b32_e32 v174, 0, v176, vcc
	v_add_f32_e32 v153, v174, v153
	v_cndmask_b32_e64 v152, v152, v153, s[28:29]
	v_cndmask_b32_e64 v153, v84, v180, s[12:13]
	v_sub_f32_e32 v154, v153, v133
	v_exp_f32_e32 v154, v154
	v_sub_f32_e32 v176, v155, v133
	v_cmp_lt_f32_e32 vcc, s89, v153
	v_exp_f32_e32 v177, v176
	v_sub_f32_e32 v179, v178, v133
	v_cndmask_b32_e32 v176, 0, v154, vcc
	v_cndmask_b32_e64 v154, v86, v182, s[12:13]
	v_cmp_lt_f32_e32 vcc, s89, v155
	v_sub_f32_e32 v155, v154, v133
	v_exp_f32_e32 v155, v155
	v_exp_f32_e32 v179, v179
	v_add_f32_e32 v153, v176, v152
	v_cndmask_b32_e32 v177, 0, v177, vcc
	v_cmp_lt_f32_e32 vcc, s89, v154
	v_add_f32_e32 v153, v177, v153
	v_cndmask_b32_e64 v180, v91, v190, s[26:27]
	v_cndmask_b32_e32 v186, 0, v155, vcc
	v_cmp_lt_f32_e32 vcc, s89, v178
	v_add_f32_e32 v153, v186, v153
	v_cndmask_b32_e64 v155, v89, v188, s[26:27]
	v_cndmask_b32_e32 v185, 0, v179, vcc
	v_add_f32_e32 v153, v185, v153
	v_cndmask_b32_e64 v152, v152, v153, s[12:13]
	v_cndmask_b32_e64 v153, v88, v184, s[26:27]
	v_sub_f32_e32 v154, v153, v133
	v_exp_f32_e32 v154, v154
	v_sub_f32_e32 v178, v155, v133
	v_cmp_lt_f32_e32 vcc, s89, v153
	v_exp_f32_e32 v179, v178
	v_sub_f32_e32 v181, v180, v133
	v_cndmask_b32_e32 v178, 0, v154, vcc
	v_cndmask_b32_e64 v154, v90, v189, s[26:27]
	v_cmp_lt_f32_e32 vcc, s89, v155
	v_sub_f32_e32 v155, v154, v133
	v_exp_f32_e32 v155, v155
	v_exp_f32_e32 v182, v181
	v_add_f32_e32 v153, v178, v152
	v_cndmask_b32_e32 v179, 0, v179, vcc
	v_cmp_lt_f32_e32 vcc, s89, v154
	v_add_f32_e32 v153, v179, v153
	v_sub_f32_e32 v154, v151, v133
	v_cndmask_b32_e32 v181, 0, v155, vcc
	v_cmp_lt_f32_e32 vcc, s89, v180
	v_add_f32_e32 v153, v181, v153
	v_exp_f32_e32 v154, v154
	v_cndmask_b32_e32 v180, 0, v182, vcc
	v_add_f32_e32 v153, v180, v153
	v_cndmask_b32_e64 v152, v152, v153, s[26:27]
	v_sub_f32_e32 v153, v150, v133
	v_exp_f32_e32 v153, v153
	v_cmp_lt_f32_e32 vcc, s89, v150
	s_nop 1
	v_cndmask_b32_e32 v182, 0, v153, vcc
	v_cmp_lt_f32_e32 vcc, s89, v151
	v_sub_f32_e32 v151, v148, v133
	v_exp_f32_e32 v151, v151
	v_cndmask_b32_e32 v183, 0, v154, vcc
	v_sub_f32_e32 v153, v149, v133
	v_cmp_lt_f32_e32 vcc, s89, v148
	v_exp_f32_e32 v153, v153
	v_add_f32_e32 v150, v182, v152
	v_cndmask_b32_e32 v184, 0, v151, vcc
	v_cmp_lt_f32_e32 vcc, s89, v149
	v_sub_f32_e32 v149, v139, v133
	v_exp_f32_e32 v149, v149
	v_add_f32_e32 v150, v183, v150
	v_add_f32_e32 v148, v184, v150
	v_cndmask_b32_e32 v223, 0, v153, vcc
	v_sub_f32_e32 v150, v147, v133
	v_cmp_lt_f32_e32 vcc, s89, v139
	v_exp_f32_e32 v150, v150
	v_add_f32_e32 v148, v223, v148
	v_cndmask_b32_e32 v188, 0, v149, vcc
	v_cmp_lt_f32_e32 vcc, s89, v147
	v_sub_f32_e32 v147, v135, v133
	v_exp_f32_e32 v147, v147
	v_cndmask_b32_e32 v189, 0, v150, vcc
	v_sub_f32_e32 v149, v138, v133
	v_cmp_lt_f32_e32 vcc, s89, v135
	v_exp_f32_e32 v149, v149
	v_cndmask_b32_e64 v148, v152, v148, s[10:11]
	v_cndmask_b32_e32 v191, 0, v147, vcc
	v_cmp_lt_f32_e32 vcc, s89, v138
	v_sub_f32_e32 v138, v130, v133
	v_exp_f32_e32 v138, v138
	v_add_f32_e32 v139, v188, v148
	v_add_f32_e32 v139, v189, v139
	v_add_f32_e32 v135, v191, v139
	v_cndmask_b32_e32 v190, 0, v149, vcc
	v_sub_f32_e32 v139, v132, v133
	v_cmp_lt_f32_e32 vcc, s89, v130
	v_exp_f32_e32 v139, v139
	v_add_f32_e32 v135, v190, v135
	v_cndmask_b32_e32 v192, 0, v138, vcc
	v_cmp_lt_f32_e32 vcc, s89, v132
	v_sub_f32_e32 v132, v17, v133
	v_exp_f32_e32 v132, v132
	v_cndmask_b32_e32 v193, 0, v139, vcc
	v_sub_f32_e32 v138, v19, v133
	v_cmp_lt_f32_e32 vcc, s89, v17
	v_exp_f32_e32 v138, v138
	v_cndmask_b32_e64 v135, v148, v135, s[24:25]
	v_cndmask_b32_e32 v222, 0, v132, vcc
	v_cmp_lt_f32_e32 vcc, s89, v19
	v_sub_f32_e32 v19, v14, v133
	v_exp_f32_e32 v19, v19
	v_add_f32_e32 v130, v192, v135
	v_add_f32_e32 v130, v193, v130
	v_add_f32_e32 v17, v222, v130
	v_cndmask_b32_e32 v221, 0, v138, vcc
	v_sub_f32_e32 v130, v15, v133
	v_cmp_lt_f32_e32 vcc, s89, v14
	v_exp_f32_e32 v130, v130
	v_add_f32_e32 v17, v221, v17
	v_cndmask_b32_e32 v194, 0, v19, vcc
	v_cmp_lt_f32_e32 vcc, s89, v15
	v_sub_f32_e32 v15, v12, v133
	v_exp_f32_e32 v15, v15
	v_cndmask_b32_e32 v195, 0, v130, vcc
	v_sub_f32_e32 v19, v13, v133
	v_cmp_lt_f32_e32 vcc, s89, v12
	v_exp_f32_e32 v19, v19
	v_cndmask_b32_e64 v17, v135, v17, s[8:9]
	v_cndmask_b32_e32 v197, 0, v15, vcc
	v_cmp_lt_f32_e32 vcc, s89, v13
	v_sub_f32_e32 v13, v10, v133
	v_exp_f32_e32 v13, v13
	v_add_f32_e32 v14, v194, v17
	v_add_f32_e32 v14, v195, v14
	v_add_f32_e32 v12, v197, v14
	v_cndmask_b32_e32 v196, 0, v19, vcc
	v_sub_f32_e32 v14, v11, v133
	v_cmp_lt_f32_e32 vcc, s89, v10
	v_exp_f32_e32 v14, v14
	v_add_f32_e32 v12, v196, v12
	v_cndmask_b32_e32 v198, 0, v13, vcc
	v_cmp_lt_f32_e32 vcc, s89, v11
	v_sub_f32_e32 v11, v8, v133
	v_exp_f32_e32 v11, v11
	v_sub_f32_e32 v13, v9, v133
	v_exp_f32_e32 v13, v13
	v_cndmask_b32_e64 v12, v17, v12, s[22:23]
	v_add_f32_e32 v10, v198, v12
	v_cndmask_b32_e32 v199, 0, v14, vcc
	v_cmp_lt_f32_e32 vcc, s89, v8
	v_add_f32_e32 v10, v199, v10
	s_nop 0
	v_cndmask_b32_e32 v220, 0, v11, vcc
	v_cmp_lt_f32_e32 vcc, s89, v9
	v_add_f32_e32 v8, v220, v10
	s_nop 0
	v_cndmask_b32_e32 v219, 0, v13, vcc
	v_add_f32_e32 v8, v219, v8
	v_cndmask_b32_e64 v8, v12, v8, s[6:7]
	ds_bpermute_b32 v9, v216, v8
	s_waitcnt lgkmcnt(0)
	v_add_f32_e32 v8, v8, v9
	ds_bpermute_b32 v9, v217, v8
	s_waitcnt lgkmcnt(0)
	v_add_f32_e32 v8, v8, v9
	v_div_scale_f32 v9, s[40:41], v8, v8, 1.0
	v_rcp_f32_e32 v10, v9
	v_readlane_b32 s40, v255, 33
	v_readlane_b32 s41, v255, 34
	v_fma_f32 v11, -v9, v10, 1.0
	v_fmac_f32_e32 v10, v11, v10
	v_div_scale_f32 v11, vcc, 1.0, v8, 1.0
	v_mul_f32_e32 v12, v11, v10
	v_fma_f32 v13, -v9, v12, v11
	v_fmac_f32_e32 v12, v13, v10
	v_fma_f32 v9, -v9, v12, v11
	v_div_fmas_f32 v9, v9, v10, v12
	v_div_fixup_f32 v9, v9, v8, 1.0
	v_cmp_lt_f32_e32 vcc, 0, v8
	v_cndmask_b32_e64 v8, v50, v18, s[38:39]
	v_lshl_add_u64 v[148:149], v[4:5], 1, s[40:41]
	v_cndmask_b32_e32 v152, 0, v9, vcc
	v_cndmask_b32_e64 v9, v51, v134, s[38:39]
	v_pk_mul_f32 v[6:7], v[152:153], v[6:7] op_sel_hi:[0,1]
	v_pk_mul_f32 v[8:9], v[152:153], v[8:9] op_sel_hi:[0,1]
	v_cndmask_b32_e64 v135, v51, v9, s[38:39]
	v_cndmask_b32_e64 v134, v50, v8, s[38:39]
	v_cndmask_b32_e64 v139, v49, v7, s[38:39]
	v_cndmask_b32_e64 v138, v48, v6, s[38:39]
	v_cndmask_b32_e64 v7, v55, v205, s[20:21]
	v_cndmask_b32_e64 v6, v54, v204, s[20:21]
	v_cndmask_b32_e64 v9, v53, v131, s[20:21]
	v_cndmask_b32_e64 v8, v52, v16, s[20:21]
	v_pk_mul_f32 v[8:9], v[152:153], v[8:9] op_sel_hi:[0,1]
	v_pk_mul_f32 v[6:7], v[152:153], v[6:7] op_sel_hi:[0,1]
	v_lshlrev_b32_e32 v4, 8, v121
	v_cndmask_b32_e64 v5, 0, 1, s[38:39]
	v_cndmask_b32_e64 v131, v55, v7, s[20:21]
	v_cndmask_b32_e64 v130, v54, v6, s[20:21]
	v_cndmask_b32_e64 v133, v53, v9, s[20:21]
	v_cndmask_b32_e64 v132, v52, v8, s[20:21]
	v_cmp_ne_u32_e64 s[40:41], 1, v5
	s_andn2_b64 vcc, exec, s[38:39]
	v_lshlrev_b32_e32 v150, 1, v4
	s_cbranch_vccnz .LBB0_449
	v_mov_b32_e32 v151, v137
	v_lshl_add_u64 v[154:155], v[148:149], 0, v[150:151]
	ds_read_b128 v[4:7], v253
	ds_read_b128 v[8:11], v253 offset:8704
	ds_read_b128 v[12:15], v253 offset:17408
	ds_read_b128 v[224:227], v253 offset:26112
	v_cvt_pk_bf16_f32 v16, v138, v139
	v_cvt_pk_bf16_f32 v17, v134, v135
	v_cvt_pk_bf16_f32 v18, v132, v133
	v_cvt_pk_bf16_f32 v19, v130, v131
	s_waitcnt vmcnt(0) lgkmcnt(0)
	s_nop 0
	v_mfma_f32_16x16x32_bf16 v[4:7], v[4:7], v[16:19], 0
	v_mfma_f32_16x16x32_bf16 v[8:11], v[8:11], v[16:19], 0
	v_mfma_f32_16x16x32_bf16 v[12:15], v[12:15], v[16:19], 0
	v_mfma_f32_16x16x32_bf16 v[16:19], v[224:227], v[16:19], 0
	s_branch .LBB0_450

.LBB0_450:
	v_cndmask_b32_e64 v141, v57, v141, s[36:37]
	v_cndmask_b32_e64 v140, v56, v140, s[36:37]
	v_mov_b32_e32 v153, v152
	v_cndmask_b32_e64 v141, v57, v141, s[36:37]
	v_cndmask_b32_e64 v140, v56, v140, s[36:37]
	v_cndmask_b32_e64 v154, v58, v143, s[36:37]
	v_cndmask_b32_e64 v224, v62, v146, s[18:19]
	v_cndmask_b32_e64 v143, v61, v145, s[18:19]
	v_cndmask_b32_e64 v226, v60, v144, s[18:19]
	v_pk_mul_f32 v[140:141], v[152:153], v[140:141]
	v_cndmask_b32_e64 v145, v59, v142, s[36:37]
	v_cndmask_b32_e64 v144, v58, v154, s[36:37]
	v_mov_b32_e32 v154, v152
	v_mov_b32_e32 v155, v152
	v_cndmask_b32_e64 v147, v57, v141, s[36:37]
	v_cndmask_b32_e64 v146, v56, v140, s[36:37]
	v_cndmask_b32_e64 v141, v63, v171, s[18:19]
	v_cndmask_b32_e64 v140, v62, v224, s[18:19]
	v_cndmask_b32_e64 v143, v61, v143, s[18:19]
	v_cndmask_b32_e64 v142, v60, v226, s[18:19]
	v_pk_mul_f32 v[144:145], v[154:155], v[144:145]
	v_pk_mul_f32 v[142:143], v[152:153], v[142:143]
	v_pk_mul_f32 v[140:141], v[154:155], v[140:141]
	v_cndmask_b32_e64 v151, 0, 1, s[36:37]
	v_cndmask_b32_e64 v145, v59, v145, s[36:37]
	v_cndmask_b32_e64 v144, v58, v144, s[36:37]
	v_cndmask_b32_e64 v141, v63, v141, s[18:19]
	v_cndmask_b32_e64 v140, v62, v140, s[18:19]
	v_cndmask_b32_e64 v143, v61, v143, s[18:19]
	v_cmp_ne_u32_e64 s[38:39], 1, v151
	s_andn2_b64 vcc, exec, s[36:37]
	v_cndmask_b32_e64 v142, v60, v142, s[18:19]
	s_cbranch_vccnz .LBB0_452
	v_mov_b32_e32 v151, v137
	ds_read_b128 v[228:231], v253 offset:64
	ds_read_b128 v[208:211], v253 offset:8768
	ds_read_b128 v[212:215], v253 offset:17472
	ds_read_b128 v[232:235], v253 offset:26176
	v_cvt_pk_bf16_f32 v224, v146, v147
	v_cvt_pk_bf16_f32 v225, v144, v145
	v_cvt_pk_bf16_f32 v226, v142, v143
	v_cvt_pk_bf16_f32 v227, v140, v141
	s_waitcnt vmcnt(0) lgkmcnt(0)
	s_nop 0
	v_mfma_f32_16x16x32_bf16 v[4:7], v[228:231], v[224:227], v[4:7]
	v_mfma_f32_16x16x32_bf16 v[8:11], v[208:211], v[224:227], v[8:11]
	v_mfma_f32_16x16x32_bf16 v[12:15], v[212:215], v[224:227], v[12:15]
	v_mfma_f32_16x16x32_bf16 v[16:19], v[232:235], v[224:227], v[16:19]
.LBB0_452:
	v_cndmask_b32_e64 v224, v66, v159, s[34:35]
	v_cndmask_b32_e64 v151, v65, v157, s[34:35]
	v_cndmask_b32_e64 v156, v64, v156, s[34:35]
	v_cndmask_b32_e64 v170, v70, v170, s[16:17]
	v_cndmask_b32_e64 v157, v69, v161, s[16:17]
	v_cndmask_b32_e64 v226, v68, v160, s[16:17]
	v_cndmask_b32_e64 v159, v67, v158, s[34:35]
	v_cndmask_b32_e64 v158, v66, v224, s[34:35]
	v_cndmask_b32_e64 v161, v65, v151, s[34:35]
	v_cndmask_b32_e64 v160, v64, v156, s[34:35]
	v_cndmask_b32_e64 v171, v71, v169, s[16:17]
	v_cndmask_b32_e64 v170, v70, v170, s[16:17]
	v_cndmask_b32_e64 v157, v69, v157, s[16:17]
	v_cndmask_b32_e64 v156, v68, v226, s[16:17]
	v_pk_mul_f32 v[160:161], v[152:153], v[160:161]
	v_pk_mul_f32 v[158:159], v[154:155], v[158:159]
	v_pk_mul_f32 v[156:157], v[152:153], v[156:157]
	v_pk_mul_f32 v[154:155], v[154:155], v[170:171]
	v_cndmask_b32_e64 v151, 0, 1, s[34:35]
	v_cndmask_b32_e64 v159, v67, v159, s[34:35]
	v_cndmask_b32_e64 v158, v66, v158, s[34:35]
	v_cndmask_b32_e64 v161, v65, v161, s[34:35]
	v_cndmask_b32_e64 v160, v64, v160, s[34:35]
	v_cndmask_b32_e64 v155, v71, v155, s[16:17]
	v_cndmask_b32_e64 v154, v70, v154, s[16:17]
	v_cndmask_b32_e64 v157, v69, v157, s[16:17]
	v_cmp_ne_u32_e64 s[36:37], 1, v151
	s_andn2_b64 vcc, exec, s[34:35]
	v_cndmask_b32_e64 v156, v68, v156, s[16:17]
	s_cbranch_vccnz .LBB0_454
	v_mov_b32_e32 v151, v137
	ds_read_b128 v[228:231], v253 offset:128
	ds_read_b128 v[208:211], v253 offset:8832
	ds_read_b128 v[212:215], v253 offset:17536
	ds_read_b128 v[232:235], v253 offset:26240
	v_cvt_pk_bf16_f32 v224, v160, v161
	v_cvt_pk_bf16_f32 v225, v158, v159
	v_cvt_pk_bf16_f32 v226, v156, v157
	v_cvt_pk_bf16_f32 v227, v154, v155
	s_waitcnt vmcnt(0) lgkmcnt(0)
	s_nop 0
	v_mfma_f32_16x16x32_bf16 v[4:7], v[228:231], v[224:227], v[4:7]
	v_mfma_f32_16x16x32_bf16 v[8:11], v[208:211], v[224:227], v[8:11]
	v_mfma_f32_16x16x32_bf16 v[12:15], v[212:215], v[224:227], v[12:15]
	v_mfma_f32_16x16x32_bf16 v[16:19], v[232:235], v[224:227], v[16:19]
.LBB0_454:
	v_cndmask_b32_e64 v170, v74, v165, s[30:31]
	v_cndmask_b32_e64 v151, v73, v163, s[30:31]
	v_cndmask_b32_e64 v162, v72, v162, s[30:31]
	v_cndmask_b32_e64 v165, v75, v164, s[30:31]
	v_cndmask_b32_e64 v164, v74, v170, s[30:31]
	v_mov_b32_e32 v170, v152
	v_mov_b32_e32 v171, v152
	v_cndmask_b32_e64 v224, v78, v168, s[14:15]
	v_cndmask_b32_e64 v163, v77, v167, s[14:15]
	v_cndmask_b32_e64 v226, v76, v166, s[14:15]
	v_cndmask_b32_e64 v167, v73, v151, s[30:31]
	v_cndmask_b32_e64 v166, v72, v162, s[30:31]
	v_pk_mul_f32 v[164:165], v[170:171], v[164:165]
	v_pk_mul_f32 v[168:169], v[152:153], v[166:167]
	v_cndmask_b32_e64 v167, v75, v165, s[30:31]
	v_cndmask_b32_e64 v166, v74, v164, s[30:31]
	v_cndmask_b32_e64 v165, v79, v187, s[14:15]
	v_cndmask_b32_e64 v164, v78, v224, s[14:15]
	v_cndmask_b32_e64 v163, v77, v163, s[14:15]
	v_cndmask_b32_e64 v162, v76, v226, s[14:15]
	v_pk_mul_f32 v[204:205], v[152:153], v[162:163]
	v_pk_mul_f32 v[162:163], v[170:171], v[164:165]
	v_cndmask_b32_e64 v151, 0, 1, s[30:31]
	v_cndmask_b32_e64 v169, v73, v169, s[30:31]
	v_cndmask_b32_e64 v168, v72, v168, s[30:31]
	v_cndmask_b32_e64 v163, v79, v163, s[14:15]
	v_cndmask_b32_e64 v162, v78, v162, s[14:15]
	v_cndmask_b32_e64 v165, v77, v205, s[14:15]
	v_cmp_ne_u32_e64 s[34:35], 1, v151
	s_andn2_b64 vcc, exec, s[30:31]
	v_cndmask_b32_e64 v164, v76, v204, s[14:15]
	s_cbranch_vccnz .LBB0_456
	v_mov_b32_e32 v151, v137
	ds_read_b128 v[228:231], v253 offset:192
	ds_read_b128 v[208:211], v253 offset:8896
	ds_read_b128 v[212:215], v253 offset:17600
	ds_read_b128 v[232:235], v253 offset:26304
	v_cvt_pk_bf16_f32 v224, v168, v169
	v_cvt_pk_bf16_f32 v225, v166, v167
	v_cvt_pk_bf16_f32 v226, v164, v165
	v_cvt_pk_bf16_f32 v227, v162, v163
	s_waitcnt vmcnt(0) lgkmcnt(0)
	s_nop 0
	v_mfma_f32_16x16x32_bf16 v[4:7], v[228:231], v[224:227], v[4:7]
	v_mfma_f32_16x16x32_bf16 v[8:11], v[208:211], v[224:227], v[8:11]
	v_mfma_f32_16x16x32_bf16 v[12:15], v[212:215], v[224:227], v[12:15]
	v_mfma_f32_16x16x32_bf16 v[16:19], v[232:235], v[224:227], v[16:19]
.LBB0_456:
	v_cndmask_b32_e64 v224, v82, v175, s[28:29]
	v_cndmask_b32_e64 v151, v81, v173, s[28:29]
	v_cndmask_b32_e64 v172, v80, v172, s[28:29]
	v_cndmask_b32_e64 v186, v86, v186, s[12:13]
	v_cndmask_b32_e64 v173, v85, v177, s[12:13]
	v_cndmask_b32_e64 v226, v84, v176, s[12:13]
	v_cndmask_b32_e64 v175, v83, v174, s[28:29]
	v_cndmask_b32_e64 v174, v82, v224, s[28:29]
	v_cndmask_b32_e64 v177, v81, v151, s[28:29]
	v_cndmask_b32_e64 v176, v80, v172, s[28:29]
	v_cndmask_b32_e64 v187, v87, v185, s[12:13]
	v_cndmask_b32_e64 v186, v86, v186, s[12:13]
	v_cndmask_b32_e64 v173, v85, v173, s[12:13]
	v_cndmask_b32_e64 v172, v84, v226, s[12:13]
	v_pk_mul_f32 v[176:177], v[152:153], v[176:177]
	v_pk_mul_f32 v[174:175], v[170:171], v[174:175]
	v_pk_mul_f32 v[172:173], v[152:153], v[172:173]
	v_pk_mul_f32 v[170:171], v[170:171], v[186:187]
	v_cndmask_b32_e64 v151, 0, 1, s[28:29]
	v_cndmask_b32_e64 v175, v83, v175, s[28:29]
	v_cndmask_b32_e64 v174, v82, v174, s[28:29]
	v_cndmask_b32_e64 v177, v81, v177, s[28:29]
	v_cndmask_b32_e64 v176, v80, v176, s[28:29]
	v_cndmask_b32_e64 v171, v87, v171, s[12:13]
	v_cndmask_b32_e64 v170, v86, v170, s[12:13]
	v_cndmask_b32_e64 v173, v85, v173, s[12:13]
	v_cmp_ne_u32_e64 s[30:31], 1, v151
	s_andn2_b64 vcc, exec, s[28:29]
	v_cndmask_b32_e64 v172, v84, v172, s[12:13]
	s_cbranch_vccnz .LBB0_458
	v_mov_b32_e32 v151, v137
	ds_read_b128 v[228:231], v253 offset:256
	ds_read_b128 v[208:211], v253 offset:8960
	ds_read_b128 v[212:215], v253 offset:17664
	ds_read_b128 v[232:235], v253 offset:26368
	v_cvt_pk_bf16_f32 v224, v176, v177
	v_cvt_pk_bf16_f32 v225, v174, v175
	v_cvt_pk_bf16_f32 v226, v172, v173
	v_cvt_pk_bf16_f32 v227, v170, v171
	s_waitcnt vmcnt(0) lgkmcnt(0)
	s_nop 0
	v_mfma_f32_16x16x32_bf16 v[4:7], v[228:231], v[224:227], v[4:7]
	v_mfma_f32_16x16x32_bf16 v[8:11], v[208:211], v[224:227], v[8:11]
	v_mfma_f32_16x16x32_bf16 v[12:15], v[212:215], v[224:227], v[12:15]
	v_mfma_f32_16x16x32_bf16 v[16:19], v[232:235], v[224:227], v[16:19]
.LBB0_458:
	v_cndmask_b32_e64 v186, v90, v181, s[26:27]
	v_cndmask_b32_e64 v151, v89, v179, s[26:27]
	v_cndmask_b32_e64 v178, v88, v178, s[26:27]
	v_cndmask_b32_e64 v181, v91, v180, s[26:27]
	v_cndmask_b32_e64 v180, v90, v186, s[26:27]
	v_mov_b32_e32 v186, v152
	v_mov_b32_e32 v187, v152
	v_cndmask_b32_e64 v224, v94, v184, s[10:11]
	v_cndmask_b32_e64 v179, v93, v183, s[10:11]
	v_cndmask_b32_e64 v226, v92, v182, s[10:11]
	v_cndmask_b32_e64 v183, v89, v151, s[26:27]
	v_cndmask_b32_e64 v182, v88, v178, s[26:27]
	v_pk_mul_f32 v[180:181], v[186:187], v[180:181]
	v_pk_mul_f32 v[184:185], v[152:153], v[182:183]
	v_cndmask_b32_e64 v183, v91, v181, s[26:27]
	v_cndmask_b32_e64 v182, v90, v180, s[26:27]
	v_cndmask_b32_e64 v181, v95, v223, s[10:11]
	v_cndmask_b32_e64 v180, v94, v224, s[10:11]
	v_cndmask_b32_e64 v179, v93, v179, s[10:11]
	v_cndmask_b32_e64 v178, v92, v226, s[10:11]
	v_pk_mul_f32 v[204:205], v[152:153], v[178:179]
	v_pk_mul_f32 v[178:179], v[186:187], v[180:181]
	v_cndmask_b32_e64 v151, 0, 1, s[26:27]
	v_cndmask_b32_e64 v185, v89, v185, s[26:27]
	v_cndmask_b32_e64 v184, v88, v184, s[26:27]
	v_cndmask_b32_e64 v179, v95, v179, s[10:11]
	v_cndmask_b32_e64 v178, v94, v178, s[10:11]
	v_cndmask_b32_e64 v181, v93, v205, s[10:11]
	v_cmp_ne_u32_e64 s[28:29], 1, v151
	s_andn2_b64 vcc, exec, s[26:27]
	v_cndmask_b32_e64 v180, v92, v204, s[10:11]
	s_cbranch_vccnz .LBB0_460
	v_mov_b32_e32 v151, v137
	ds_read_b128 v[228:231], v253 offset:320
	ds_read_b128 v[208:211], v253 offset:9024
	ds_read_b128 v[212:215], v253 offset:17728
	ds_read_b128 v[232:235], v253 offset:26432
	v_cvt_pk_bf16_f32 v224, v184, v185
	v_cvt_pk_bf16_f32 v225, v182, v183
	v_cvt_pk_bf16_f32 v226, v180, v181
	v_cvt_pk_bf16_f32 v227, v178, v179
	s_waitcnt vmcnt(0) lgkmcnt(0)
	s_nop 0
	v_mfma_f32_16x16x32_bf16 v[4:7], v[228:231], v[224:227], v[4:7]
	v_mfma_f32_16x16x32_bf16 v[8:11], v[208:211], v[224:227], v[8:11]
	v_mfma_f32_16x16x32_bf16 v[12:15], v[212:215], v[224:227], v[12:15]
	v_mfma_f32_16x16x32_bf16 v[16:19], v[232:235], v[224:227], v[16:19]
.LBB0_460:
	v_cndmask_b32_e64 v224, v98, v191, s[24:25]
	v_cndmask_b32_e64 v151, v97, v189, s[24:25]
	v_cndmask_b32_e64 v188, v96, v188, s[24:25]
	v_cndmask_b32_e64 v222, v102, v222, s[8:9]
	v_cndmask_b32_e64 v189, v101, v193, s[8:9]
	v_cndmask_b32_e64 v226, v100, v192, s[8:9]
	v_cndmask_b32_e64 v191, v99, v190, s[24:25]
	v_cndmask_b32_e64 v190, v98, v224, s[24:25]
	v_cndmask_b32_e64 v193, v97, v151, s[24:25]
	v_cndmask_b32_e64 v192, v96, v188, s[24:25]
	v_cndmask_b32_e64 v205, v103, v221, s[8:9]
	v_cndmask_b32_e64 v204, v102, v222, s[8:9]
	v_cndmask_b32_e64 v189, v101, v189, s[8:9]
	v_cndmask_b32_e64 v188, v100, v226, s[8:9]
	v_pk_mul_f32 v[192:193], v[152:153], v[192:193]
	v_pk_mul_f32 v[190:191], v[186:187], v[190:191]
	v_pk_mul_f32 v[188:189], v[152:153], v[188:189]
	v_pk_mul_f32 v[186:187], v[186:187], v[204:205]
	v_cndmask_b32_e64 v151, 0, 1, s[24:25]
	v_cndmask_b32_e64 v191, v99, v191, s[24:25]
	v_cndmask_b32_e64 v190, v98, v190, s[24:25]
	v_cndmask_b32_e64 v193, v97, v193, s[24:25]
	v_cndmask_b32_e64 v192, v96, v192, s[24:25]
	v_cndmask_b32_e64 v187, v103, v187, s[8:9]
	v_cndmask_b32_e64 v186, v102, v186, s[8:9]
	v_cndmask_b32_e64 v189, v101, v189, s[8:9]
	v_cmp_ne_u32_e64 s[26:27], 1, v151
	s_andn2_b64 vcc, exec, s[24:25]
	v_cndmask_b32_e64 v188, v100, v188, s[8:9]
	s_cbranch_vccnz .LBB0_462
	v_mov_b32_e32 v151, v137
	ds_read_b128 v[226:229], v253 offset:384
	ds_read_b128 v[208:211], v253 offset:9088
	ds_read_b128 v[212:215], v253 offset:17792
	ds_read_b128 v[232:235], v253 offset:26496
	v_cvt_pk_bf16_f32 v222, v192, v193
	v_cvt_pk_bf16_f32 v223, v190, v191
	v_cvt_pk_bf16_f32 v224, v188, v189
	v_cvt_pk_bf16_f32 v225, v186, v187
	s_waitcnt vmcnt(0) lgkmcnt(0)
	s_nop 0
	v_mfma_f32_16x16x32_bf16 v[4:7], v[226:229], v[222:225], v[4:7]
	v_mfma_f32_16x16x32_bf16 v[8:11], v[208:211], v[222:225], v[8:11]
	v_mfma_f32_16x16x32_bf16 v[12:15], v[212:215], v[222:225], v[12:15]
	v_mfma_f32_16x16x32_bf16 v[16:19], v[232:235], v[222:225], v[16:19]
.LBB0_462:
	v_cndmask_b32_e64 v222, v106, v197, s[22:23]
	v_cndmask_b32_e64 v151, v105, v195, s[22:23]
	v_cndmask_b32_e64 v194, v104, v194, s[22:23]
	v_cndmask_b32_e64 v220, v110, v220, s[6:7]
	v_cndmask_b32_e64 v195, v109, v199, s[6:7]
	v_cndmask_b32_e64 v224, v108, v198, s[6:7]
	v_cndmask_b32_e64 v197, v107, v196, s[22:23]
	v_cndmask_b32_e64 v196, v106, v222, s[22:23]
	v_cndmask_b32_e64 v199, v105, v151, s[22:23]
	v_cndmask_b32_e64 v198, v104, v194, s[22:23]
	v_mov_b32_e32 v204, v152
	v_mov_b32_e32 v205, v152
	v_cndmask_b32_e64 v207, v111, v219, s[6:7]
	v_cndmask_b32_e64 v206, v110, v220, s[6:7]
	v_cndmask_b32_e64 v195, v109, v195, s[6:7]
	v_cndmask_b32_e64 v194, v108, v224, s[6:7]
	v_pk_mul_f32 v[198:199], v[152:153], v[198:199]
	v_pk_mul_f32 v[196:197], v[204:205], v[196:197]
	v_pk_mul_f32 v[194:195], v[152:153], v[194:195]
	v_pk_mul_f32 v[152:153], v[204:205], v[206:207]
	v_cndmask_b32_e64 v151, 0, 1, s[22:23]
	v_cndmask_b32_e64 v197, v107, v197, s[22:23]
	v_cndmask_b32_e64 v196, v106, v196, s[22:23]
	v_cndmask_b32_e64 v199, v105, v199, s[22:23]
	v_cndmask_b32_e64 v198, v104, v198, s[22:23]
	v_cndmask_b32_e64 v153, v111, v153, s[6:7]
	v_cndmask_b32_e64 v152, v110, v152, s[6:7]
	v_cndmask_b32_e64 v195, v109, v195, s[6:7]
	v_cmp_ne_u32_e64 s[24:25], 1, v151
	s_andn2_b64 vcc, exec, s[22:23]
	v_cndmask_b32_e64 v194, v108, v194, s[6:7]
	s_cbranch_vccnz .LBB0_464
	v_mov_b32_e32 v151, v137
	ds_read_b128 v[148:151], v253 offset:448
	ds_read_b128 v[208:211], v253 offset:9152
	ds_read_b128 v[212:215], v253 offset:17856
	ds_read_b128 v[232:235], v253 offset:26560
	v_cvt_pk_bf16_f32 v220, v198, v199
	v_cvt_pk_bf16_f32 v221, v196, v197
	v_cvt_pk_bf16_f32 v222, v194, v195
	v_cvt_pk_bf16_f32 v223, v152, v153
	s_waitcnt vmcnt(0) lgkmcnt(0)
	s_nop 0
	v_mfma_f32_16x16x32_bf16 v[4:7], v[148:151], v[220:223], v[4:7]
	v_mfma_f32_16x16x32_bf16 v[8:11], v[208:211], v[220:223], v[8:11]
	v_mfma_f32_16x16x32_bf16 v[12:15], v[212:215], v[220:223], v[12:15]
	v_mfma_f32_16x16x32_bf16 v[16:19], v[232:235], v[220:223], v[16:19]

.LBB0_870:
	s_lshl_b32 s18, s42, 8
	v_mbcnt_lo_u32_b32 v141, -1, 0
	v_mbcnt_hi_u32_b32 v141, -1, v141
	s_add_i32 s18, s18, s35
	v_and_or_b32 v140, v141, 15, s18
	s_lshl_b32 s18, s43, 8
	v_ashrrev_i32_e32 v141, 1, v141
	v_and_b32_e32 v141, -8, v141
	s_or_b32 s18, s18, s36
	v_add_u32_e32 v144, s18, v141
	v_ashrrev_i32_e32 v141, 31, v140
	v_lshlrev_b64 v[140:141], 12, v[140:141]
	v_lshl_add_u64 v[140:141], s[6:7], 0, v[140:141]
	v_ashrrev_i32_e32 v145, 31, v144
	v_lshl_add_u64 v[140:141], v[144:145], 2, v[140:141]
	s_mov_b64 s[18:19], 0x80000
	global_load_dwordx4 v[144:147], v[140:141], off
	global_load_dwordx4 v[148:151], v[140:141], off offset:16
	global_load_dwordx4 v[152:155], v[140:141], off offset:512
	global_load_dwordx4 v[156:159], v[140:141], off offset:528
	v_add_co_u32_e32 v216, vcc, s94, v140
	v_addc_co_u32_e32 v217, vcc, 0, v141, vcc
	global_load_dwordx4 v[160:163], v[216:217], off
	global_load_dwordx4 v[164:167], v[216:217], off offset:16
	global_load_dwordx4 v[168:171], v[216:217], off offset:512
	global_load_dwordx4 v[172:175], v[216:217], off offset:528
	v_add_co_u32_e32 v216, vcc, s0, v140
	v_addc_co_u32_e32 v217, vcc, 0, v141, vcc
	global_load_dwordx4 v[176:179], v[216:217], off
	global_load_dwordx4 v[180:183], v[216:217], off offset:16
	global_load_dwordx4 v[184:187], v[216:217], off offset:512
	global_load_dwordx4 v[188:191], v[216:217], off offset:528
	v_add_co_u32_e32 v216, vcc, s1, v140
	v_addc_co_u32_e32 v217, vcc, 0, v141, vcc
	global_load_dwordx4 v[192:195], v[216:217], off
	global_load_dwordx4 v[196:199], v[216:217], off offset:16
	global_load_dwordx4 v[200:203], v[216:217], off offset:512
	s_nop 0
	global_load_dwordx4 v[216:219], v[216:217], off offset:528
	s_waitcnt vmcnt(0)
	v_pk_fma_f32 v[124:125], v[124:125], 0.5, v[144:145] op_sel_hi:[1,0,1]
	v_pk_fma_f32 v[126:127], v[126:127], 0.5, v[146:147] op_sel_hi:[1,0,1]
	v_pk_fma_f32 v[120:121], v[120:121], 0.5, v[148:149] op_sel_hi:[1,0,1]
	v_pk_fma_f32 v[122:123], v[122:123], 0.5, v[150:151] op_sel_hi:[1,0,1]
	v_pk_fma_f32 v[104:105], v[104:105], 0.5, v[152:153] op_sel_hi:[1,0,1]
	v_pk_fma_f32 v[106:107], v[106:107], 0.5, v[154:155] op_sel_hi:[1,0,1]
	v_pk_fma_f32 v[96:97], v[96:97], 0.5, v[156:157] op_sel_hi:[1,0,1]
	v_pk_fma_f32 v[98:99], v[98:99], 0.5, v[158:159] op_sel_hi:[1,0,1]
	v_pk_fma_f32 v[116:117], v[116:117], 0.5, v[160:161] op_sel_hi:[1,0,1]
	v_pk_fma_f32 v[118:119], v[118:119], 0.5, v[162:163] op_sel_hi:[1,0,1]
	v_pk_fma_f32 v[112:113], v[112:113], 0.5, v[164:165] op_sel_hi:[1,0,1]
	v_pk_fma_f32 v[114:115], v[114:115], 0.5, v[166:167] op_sel_hi:[1,0,1]
	v_pk_fma_f32 v[88:89], v[88:89], 0.5, v[168:169] op_sel_hi:[1,0,1]
	v_pk_fma_f32 v[90:91], v[90:91], 0.5, v[170:171] op_sel_hi:[1,0,1]
	v_pk_fma_f32 v[80:81], v[80:81], 0.5, v[172:173] op_sel_hi:[1,0,1]
	v_pk_fma_f32 v[82:83], v[82:83], 0.5, v[174:175] op_sel_hi:[1,0,1]
	v_pk_fma_f32 v[108:109], v[108:109], 0.5, v[176:177] op_sel_hi:[1,0,1]
	v_pk_fma_f32 v[110:111], v[110:111], 0.5, v[178:179] op_sel_hi:[1,0,1]
	v_pk_fma_f32 v[100:101], v[100:101], 0.5, v[180:181] op_sel_hi:[1,0,1]
	v_pk_fma_f32 v[102:103], v[102:103], 0.5, v[182:183] op_sel_hi:[1,0,1]
	v_pk_fma_f32 v[76:77], v[76:77], 0.5, v[184:185] op_sel_hi:[1,0,1]
	v_pk_fma_f32 v[78:79], v[78:79], 0.5, v[186:187] op_sel_hi:[1,0,1]
	v_pk_fma_f32 v[72:73], v[72:73], 0.5, v[188:189] op_sel_hi:[1,0,1]
	v_pk_fma_f32 v[74:75], v[74:75], 0.5, v[190:191] op_sel_hi:[1,0,1]
	v_pk_fma_f32 v[92:93], v[92:93], 0.5, v[192:193] op_sel_hi:[1,0,1]
	v_pk_fma_f32 v[94:95], v[94:95], 0.5, v[194:195] op_sel_hi:[1,0,1]
	v_pk_fma_f32 v[84:85], v[84:85], 0.5, v[196:197] op_sel_hi:[1,0,1]
	v_pk_fma_f32 v[86:87], v[86:87], 0.5, v[198:199] op_sel_hi:[1,0,1]
	v_pk_fma_f32 v[68:69], v[68:69], 0.5, v[200:201] op_sel_hi:[1,0,1]
	v_pk_fma_f32 v[70:71], v[70:71], 0.5, v[202:203] op_sel_hi:[1,0,1]
	v_pk_fma_f32 v[64:65], v[64:65], 0.5, v[216:217] op_sel_hi:[1,0,1]
	v_pk_fma_f32 v[66:67], v[66:67], 0.5, v[218:219] op_sel_hi:[1,0,1]
	v_lshl_add_u64 v[216:217], v[140:141], 0, s[18:19]
	global_load_dwordx4 v[144:147], v[216:217], off
	global_load_dwordx4 v[148:151], v[216:217], off offset:16
	global_load_dwordx4 v[152:155], v[216:217], off offset:512
	global_load_dwordx4 v[156:159], v[216:217], off offset:528
	v_add_co_u32_e32 v216, vcc, s94, v216
	v_addc_co_u32_e32 v217, vcc, 0, v217, vcc
	global_load_dwordx4 v[160:163], v[216:217], off
	global_load_dwordx4 v[164:167], v[216:217], off offset:16
	global_load_dwordx4 v[168:171], v[216:217], off offset:512
	global_load_dwordx4 v[172:175], v[216:217], off offset:528
	v_add_co_u32_e32 v216, vcc, s94, v216
	v_addc_co_u32_e32 v217, vcc, 0, v217, vcc
	global_load_dwordx4 v[176:179], v[216:217], off
	global_load_dwordx4 v[180:183], v[216:217], off offset:16
	global_load_dwordx4 v[184:187], v[216:217], off offset:512
	global_load_dwordx4 v[188:191], v[216:217], off offset:528
	v_add_co_u32_e32 v216, vcc, s94, v216
	v_addc_co_u32_e32 v217, vcc, 0, v217, vcc
	global_load_dwordx4 v[192:195], v[216:217], off
	global_load_dwordx4 v[196:199], v[216:217], off offset:16
	global_load_dwordx4 v[200:203], v[216:217], off offset:512
	s_nop 0
	global_load_dwordx4 v[216:219], v[216:217], off offset:528
	global_store_dwordx4 v[140:141], v[124:127], off
	global_store_dwordx4 v[140:141], v[120:123], off offset:16
	global_store_dwordx4 v[140:141], v[104:107], off offset:512
	global_store_dwordx4 v[140:141], v[96:99], off offset:528
	v_add_co_u32_e32 v124, vcc, s94, v140
	v_addc_co_u32_e32 v125, vcc, 0, v141, vcc
	global_store_dwordx4 v[124:125], v[116:119], off
	global_store_dwordx4 v[124:125], v[112:115], off offset:16
	global_store_dwordx4 v[124:125], v[88:91], off offset:512
	global_store_dwordx4 v[124:125], v[80:83], off offset:528
	v_add_co_u32_e32 v126, vcc, s0, v140
	v_addc_co_u32_e32 v127, vcc, 0, v141, vcc
	global_store_dwordx4 v[126:127], v[108:111], off
	global_store_dwordx4 v[126:127], v[100:103], off offset:16
	global_store_dwordx4 v[126:127], v[76:79], off offset:512
	global_store_dwordx4 v[126:127], v[72:75], off offset:528
	v_add_co_u32_e32 v120, vcc, s1, v140
	v_addc_co_u32_e32 v121, vcc, 0, v141, vcc
	global_store_dwordx4 v[120:121], v[92:95], off
	global_store_dwordx4 v[120:121], v[84:87], off offset:16
	global_store_dwordx4 v[120:121], v[68:71], off offset:512
	global_store_dwordx4 v[120:121], v[64:67], off offset:528
	v_lshl_add_u64 v[104:105], v[140:141], 0, s[18:19]
	v_add_co_u32_e32 v106, vcc, s94, v104
	v_addc_co_u32_e32 v107, vcc, 0, v105, vcc
	v_add_co_u32_e32 v96, vcc, s0, v104
	v_addc_co_u32_e32 v97, vcc, 0, v105, vcc
	v_add_co_u32_e32 v98, vcc, s1, v104
	v_addc_co_u32_e32 v99, vcc, 0, v105, vcc
	s_waitcnt vmcnt(16)
	v_pk_fma_f32 v[60:61], v[60:61], 0.5, v[144:145] op_sel_hi:[1,0,1]
	v_pk_fma_f32 v[62:63], v[62:63], 0.5, v[146:147] op_sel_hi:[1,0,1]
	v_pk_fma_f32 v[56:57], v[56:57], 0.5, v[148:149] op_sel_hi:[1,0,1]
	v_pk_fma_f32 v[58:59], v[58:59], 0.5, v[150:151] op_sel_hi:[1,0,1]
	v_pk_fma_f32 v[40:41], v[40:41], 0.5, v[152:153] op_sel_hi:[1,0,1]
	v_pk_fma_f32 v[42:43], v[42:43], 0.5, v[154:155] op_sel_hi:[1,0,1]
	v_pk_fma_f32 v[32:33], v[32:33], 0.5, v[156:157] op_sel_hi:[1,0,1]
	v_pk_fma_f32 v[34:35], v[34:35], 0.5, v[158:159] op_sel_hi:[1,0,1]
	v_pk_fma_f32 v[52:53], v[52:53], 0.5, v[160:161] op_sel_hi:[1,0,1]
	v_pk_fma_f32 v[54:55], v[54:55], 0.5, v[162:163] op_sel_hi:[1,0,1]
	v_pk_fma_f32 v[48:49], v[48:49], 0.5, v[164:165] op_sel_hi:[1,0,1]
	v_pk_fma_f32 v[50:51], v[50:51], 0.5, v[166:167] op_sel_hi:[1,0,1]
	v_pk_fma_f32 v[24:25], v[24:25], 0.5, v[168:169] op_sel_hi:[1,0,1]
	v_pk_fma_f32 v[26:27], v[26:27], 0.5, v[170:171] op_sel_hi:[1,0,1]
	v_pk_fma_f32 v[20:21], v[20:21], 0.5, v[172:173] op_sel_hi:[1,0,1]
	v_pk_fma_f32 v[22:23], v[22:23], 0.5, v[174:175] op_sel_hi:[1,0,1]
	v_pk_fma_f32 v[44:45], v[44:45], 0.5, v[176:177] op_sel_hi:[1,0,1]
	v_pk_fma_f32 v[46:47], v[46:47], 0.5, v[178:179] op_sel_hi:[1,0,1]
	v_pk_fma_f32 v[36:37], v[36:37], 0.5, v[180:181] op_sel_hi:[1,0,1]
	v_pk_fma_f32 v[38:39], v[38:39], 0.5, v[182:183] op_sel_hi:[1,0,1]
	v_pk_fma_f32 v[16:17], v[16:17], 0.5, v[184:185] op_sel_hi:[1,0,1]
	v_pk_fma_f32 v[18:19], v[18:19], 0.5, v[186:187] op_sel_hi:[1,0,1]
	v_pk_fma_f32 v[12:13], v[12:13], 0.5, v[188:189] op_sel_hi:[1,0,1]
	v_pk_fma_f32 v[14:15], v[14:15], 0.5, v[190:191] op_sel_hi:[1,0,1]
	v_pk_fma_f32 v[28:29], v[28:29], 0.5, v[192:193] op_sel_hi:[1,0,1]
	v_pk_fma_f32 v[30:31], v[30:31], 0.5, v[194:195] op_sel_hi:[1,0,1]
	v_pk_fma_f32 v[8:9], v[8:9], 0.5, v[196:197] op_sel_hi:[1,0,1]
	v_pk_fma_f32 v[10:11], v[10:11], 0.5, v[198:199] op_sel_hi:[1,0,1]
	v_pk_fma_f32 v[4:5], v[4:5], 0.5, v[200:201] op_sel_hi:[1,0,1]
	v_pk_fma_f32 v[6:7], v[6:7], 0.5, v[202:203] op_sel_hi:[1,0,1]
	v_pk_fma_f32 v[0:1], v[0:1], 0.5, v[216:217] op_sel_hi:[1,0,1]
	v_pk_fma_f32 v[2:3], v[2:3], 0.5, v[218:219] op_sel_hi:[1,0,1]
	global_store_dwordx4 v[104:105], v[60:63], off
	global_store_dwordx4 v[104:105], v[56:59], off offset:16
	global_store_dwordx4 v[104:105], v[40:43], off offset:512
	global_store_dwordx4 v[104:105], v[32:35], off offset:528
	global_store_dwordx4 v[106:107], v[52:55], off
	global_store_dwordx4 v[106:107], v[48:51], off offset:16
	global_store_dwordx4 v[106:107], v[24:27], off offset:512
	global_store_dwordx4 v[106:107], v[20:23], off offset:528
	global_store_dwordx4 v[96:97], v[44:47], off
	global_store_dwordx4 v[96:97], v[36:39], off offset:16
	global_store_dwordx4 v[96:97], v[16:19], off offset:512
	global_store_dwordx4 v[96:97], v[12:15], off offset:528
	global_store_dwordx4 v[98:99], v[28:31], off
	global_store_dwordx4 v[98:99], v[8:11], off offset:16
	global_store_dwordx4 v[98:99], v[4:7], off offset:512
	global_store_dwordx4 v[98:99], v[0:3], off offset:528
	s_and_b64 vcc, exec, s[2:3]
	s_mov_b64 s[2:3], -1
	s_cbranch_vccnz .LBB0_855
	s_andn2_b64 vcc, exec, s[12:13]
	s_cbranch_vccnz .LBB0_854
	s_barrier
	s_branch .LBB0_854

	.amdhsa_kernel _Z10hybrid_fwd6Params
		.amdhsa_group_segment_fixed_size 0
		.amdhsa_private_segment_fixed_size 0
		.amdhsa_kernarg_size 448
		.amdhsa_user_sgpr_count 2
		.amdhsa_user_sgpr_dispatch_ptr 0
		.amdhsa_user_sgpr_queue_ptr 0
		.amdhsa_user_sgpr_kernarg_segment_ptr 1
		.amdhsa_user_sgpr_dispatch_id 0
		.amdhsa_user_sgpr_kernarg_preload_length 0
		.amdhsa_user_sgpr_kernarg_preload_offset 0
		.amdhsa_user_sgpr_private_segment_size 0
		.amdhsa_uses_dynamic_stack 0
		.amdhsa_enable_private_segment 0
		.amdhsa_system_sgpr_workgroup_id_x 1
		.amdhsa_system_sgpr_workgroup_id_y 0
		.amdhsa_system_sgpr_workgroup_id_z 0
		.amdhsa_system_sgpr_workgroup_info 0
		.amdhsa_system_vgpr_workitem_id 2
		.amdhsa_next_free_vgpr 256
		.amdhsa_next_free_sgpr 102
		.amdhsa_accum_offset 256
		.amdhsa_reserve_vcc 1
		.amdhsa_float_round_mode_32 0
		.amdhsa_float_round_mode_16_64 0
		.amdhsa_float_denorm_mode_32 3
		.amdhsa_float_denorm_mode_16_64 3
		.amdhsa_dx10_clamp 1
		.amdhsa_ieee_mode 1
		.amdhsa_fp16_overflow 0
		.amdhsa_tg_split 0
		.amdhsa_exception_fp_ieee_invalid_op 0
		.amdhsa_exception_fp_denorm_src 0
		.amdhsa_exception_fp_ieee_div_zero 0
		.amdhsa_exception_fp_ieee_overflow 0
		.amdhsa_exception_fp_ieee_underflow 0
		.amdhsa_exception_fp_ieee_inexact 0
		.amdhsa_exception_int_div_zero 0
	.end_amdhsa_kernel

amdhsa.kernels:
  - .agpr_count:     0
    .args:
      - .offset:         0
        .size:           192
        .value_kind:     by_value
      - .offset:         192
        .size:           4
        .value_kind:     hidden_block_count_x
      - .offset:         196
        .size:           4
        .value_kind:     hidden_block_count_y
      - .offset:         200
        .size:           4
        .value_kind:     hidden_block_count_z
      - .offset:         204
        .size:           2
        .value_kind:     hidden_group_size_x
      - .offset:         206
        .size:           2
        .value_kind:     hidden_group_size_y
      - .offset:         208
        .size:           2
        .value_kind:     hidden_group_size_z
      - .offset:         210
        .size:           2
        .value_kind:     hidden_remainder_x
      - .offset:         212
        .size:           2
        .value_kind:     hidden_remainder_y
      - .offset:         214
        .size:           2
        .value_kind:     hidden_remainder_z
      - .offset:         232
        .size:           8
        .value_kind:     hidden_global_offset_x
      - .offset:         240
        .size:           8
        .value_kind:     hidden_global_offset_y
      - .offset:         248
        .size:           8
        .value_kind:     hidden_global_offset_z
      - .offset:         256
        .size:           2
        .value_kind:     hidden_grid_dims
      - .offset:         280
        .size:           8
        .value_kind:     hidden_multigrid_sync_arg
      - .offset:         312
        .size:           4
        .value_kind:     hidden_dynamic_lds_size
    .group_segment_fixed_size: 0
    .kernarg_segment_align: 8
    .kernarg_segment_size: 448
    .language:       OpenCL C
    .language_version:
      - 2
      - 0
    .max_flat_workgroup_size: 512
    .name:           _Z10hybrid_fwd6Params
    .private_segment_fixed_size: 0
    .sgpr_count:     108
    .sgpr_spill_count: 118
    .symbol:         _Z10hybrid_fwd6Params.kd
    .uniform_work_group_size: 1
    .uses_dynamic_stack: false
    .vgpr_count:     256
    .vgpr_spill_count: 0
    .wavefront_size: 64
